# K-loop LDS-DMAs use SGPR base + 32-bit VGPR offset (saddr form) instead of 64-bit VGPR addresses: 16 v_lshl_add_u64 per iteration removed
# baseline (speedup 1.0000x reference)
; #define PG8_STAGE(bufoff, gbase, voff) do { _Pragma("unroll") for (int _i = 0; _i < 2; ++_i) \
;         __builtin_amdgcn_global_load_lds((const unsigned*)((const char*)(gbase) + (voff)[_i]), (LAS unsigned*)(lds + (bufoff) + ldsw + _i * 8192), 16, 0, 0); } while (0)
; #define PG8_LDA(dst, b, h) do { _Pragma("unroll") for (int m = 0; m < 4; ++m) _Pragma("unroll") for (int k = 0; k < 2; ++k) dst[m][k] = *(const LAS bf16x8*)(lds + PG8_SA(b, h) + aoff + m * 2048 + k * 1024); } while (0)
; #define PG8_LDB(dst, b, h) do { _Pragma("unroll") for (int n = 0; n < 2; ++n) _Pragma("unroll") for (int k = 0; k < 2; ++k) dst[n][k] = *(const LAS bf16x8*)(lds + PG8_SB(b, h) + boff + n * 2048 + k * 1024); } while (0)
; #define PG8_MMA(ai, bj, At, Bt) do { __builtin_amdgcn_s_setprio(3); _Pragma("unroll") for (int m = 0; m < 4; ++m) _Pragma("unroll") for (int n = 0; n < 2; ++n) _Pragma("unroll") for (int k = 0; k < 2; ++k) \
;         acc[ai][bj][m][n] = __builtin_amdgcn_mfma_f32_16x16x32_bf16(Bt[n][k], At[m][k], acc[ai][bj][m][n], 0, 0, 0); __builtin_amdgcn_s_setprio(0); } while (0)
; #define PG8_WAIT_V(n) asm volatile("s_waitcnt vmcnt(" #n ")" ::: "memory")
; #define PG8_WAIT_L(n) asm volatile("s_waitcnt lgkmcnt(" #n ")" ::: "memory")
; #define PG8_BAR __builtin_amdgcn_s_barrier()
; #define PG8_SCHED __builtin_amdgcn_sched_barrier(0)
; template <class Epi, class Sched, bool ALIGN_EPI = false, bool SP2 = false>
; __device__ __forceinline__ void gemm_phase(LAS unsigned char* lds, const Gemm g, const Sched& S, const Epi& E) {
;     ...
;             PG8_LDB(B0, 0, 0); PG8_LDB(B1, 0, 1); PG8_SCHED; PG8_LDA(At, 0, 0); PG8_STAGE(PG8_SA(1, 1), a1 + hsA, voffA);
;             PG8_WAIT_V(8); PG8_WAIT_L(0); PG8_BAR; PG8_MMA(0, 0, At, B0); PG8_MMA(0, 1, At, B1); PG8_BAR; PG8_SCHED;
;             PG8_LDA(At, 0, 1); PG8_STAGE(PG8_SB(0, 0), b2, voffB); PG8_STAGE(PG8_SB(0, 1), b2 + hsB, voffB); PG8_STAGE(PG8_SA(0, 0), a2, voffA);
;             PG8_WAIT_V(8); PG8_WAIT_L(0); PG8_BAR; PG8_MMA(1, 0, At, B0); PG8_MMA(1, 1, At, B1); PG8_BAR; PG8_SCHED;
.LBB0_64:
	ds_read_b128 v[128:131], v158
	ds_read_b128 v[150:153], v251
	ds_read_b128 v[166:169], v158 offset:2048
	ds_read_b128 v[170:173], v251 offset:2048
	ds_read_b128 v[174:177], v159
	ds_read_b128 v[178:181], v252
	ds_read_b128 v[182:185], v159 offset:2048
	ds_read_b128 v[186:189], v252 offset:2048
	s_add_u32 s6, s4, 0xffefc080
	s_addc_u32 s7, s5, -1
	s_cmp_eq_u32 s91, 60
	s_cselect_b32 s63, s59, s7
	s_cselect_b32 s62, s58, s6
	s_cselect_b32 s7, s61, s90
	s_cselect_b32 s6, s60, s89
	s_sub_u32 s100, s4, 0x104000
	s_subb_u32 s101, s5, 0
	s_mov_b32 m0, s76
	s_nop 0
	global_load_lds_dwordx4 v132, s[100:101]
	s_mov_b32 m0, s77
	s_nop 0
	global_load_lds_dwordx4 v136, s[100:101]
	s_add_i32 m0, s68, 0xc000
	ds_read_b128 v[190:193], v160
	ds_read_b128 v[194:197], v250
	ds_read_b128 v[198:201], v160 offset:2048
	ds_read_b128 v[206:209], v250 offset:2048
	ds_read_b128 v[210:213], v160 offset:4096
	ds_read_b128 v[214:217], v250 offset:4096
	ds_read_b128 v[218:221], v160 offset:6144
	ds_read_b128 v[222:225], v250 offset:6144
	global_load_lds_dwordx4 v142, s[4:5]
	s_add_i32 m0, s68, 0xe000
	s_nop 0
	global_load_lds_dwordx4 v144, s[4:5]
	s_waitcnt vmcnt(8)
	s_waitcnt lgkmcnt(0)
	s_barrier
	s_setprio 3
	s_waitcnt lgkmcnt(0)
	v_mfma_f32_16x16x32_bf16 v[124:127], v[128:131], v[190:193], v[124:127]
	v_mfma_f32_16x16x32_bf16 v[124:127], v[150:153], v[194:197], v[124:127]
	v_mfma_f32_16x16x32_bf16 v[120:123], v[166:169], v[190:193], v[120:123]
	v_mfma_f32_16x16x32_bf16 v[120:123], v[170:173], v[194:197], v[120:123]
	v_mfma_f32_16x16x32_bf16 v[108:111], v[128:131], v[198:201], v[108:111]
	v_mfma_f32_16x16x32_bf16 v[108:111], v[150:153], v[206:209], v[108:111]
	v_mfma_f32_16x16x32_bf16 v[104:107], v[166:169], v[198:201], v[104:107]
	v_mfma_f32_16x16x32_bf16 v[104:107], v[170:173], v[206:209], v[104:107]
	v_mfma_f32_16x16x32_bf16 v[92:95], v[128:131], v[210:213], v[92:95]
	v_mfma_f32_16x16x32_bf16 v[92:95], v[150:153], v[214:217], v[92:95]
	v_mfma_f32_16x16x32_bf16 v[88:91], v[166:169], v[210:213], v[88:91]
	v_mfma_f32_16x16x32_bf16 v[88:91], v[170:173], v[214:217], v[88:91]
	v_mfma_f32_16x16x32_bf16 v[76:79], v[128:131], v[218:221], v[76:79]
	v_mfma_f32_16x16x32_bf16 v[76:79], v[150:153], v[222:225], v[76:79]
	v_mfma_f32_16x16x32_bf16 v[72:75], v[166:169], v[218:221], v[72:75]
	v_mfma_f32_16x16x32_bf16 v[72:75], v[170:173], v[222:225], v[72:75]
	s_setprio 0
	s_setprio 3
	v_mfma_f32_16x16x32_bf16 v[116:119], v[174:177], v[190:193], v[116:119]
	v_mfma_f32_16x16x32_bf16 v[116:119], v[178:181], v[194:197], v[116:119]
	v_mfma_f32_16x16x32_bf16 v[112:115], v[182:185], v[190:193], v[112:115]
	v_mfma_f32_16x16x32_bf16 v[112:115], v[186:189], v[194:197], v[112:115]
	v_mfma_f32_16x16x32_bf16 v[100:103], v[174:177], v[198:201], v[100:103]
	v_mfma_f32_16x16x32_bf16 v[100:103], v[178:181], v[206:209], v[100:103]
	v_mfma_f32_16x16x32_bf16 v[96:99], v[182:185], v[198:201], v[96:99]
	v_mfma_f32_16x16x32_bf16 v[96:99], v[186:189], v[206:209], v[96:99]
	v_mfma_f32_16x16x32_bf16 v[84:87], v[174:177], v[210:213], v[84:87]
	v_mfma_f32_16x16x32_bf16 v[84:87], v[178:181], v[214:217], v[84:87]
	v_mfma_f32_16x16x32_bf16 v[80:83], v[182:185], v[210:213], v[80:83]
	v_mfma_f32_16x16x32_bf16 v[80:83], v[186:189], v[214:217], v[80:83]
	v_mfma_f32_16x16x32_bf16 v[68:71], v[174:177], v[218:221], v[68:71]
	v_mfma_f32_16x16x32_bf16 v[68:71], v[178:181], v[222:225], v[68:71]
	v_mfma_f32_16x16x32_bf16 v[64:67], v[182:185], v[218:221], v[64:67]
	v_mfma_f32_16x16x32_bf16 v[64:67], v[186:189], v[222:225], v[64:67]
	s_setprio 0
	s_barrier
	s_add_i32 s92, s82, s67
	s_mov_b32 m0, s92
	ds_read_b128 v[190:193], v160 offset:16384
	ds_read_b128 v[194:197], v250 offset:16384
	ds_read_b128 v[198:201], v160 offset:18432
	ds_read_b128 v[206:209], v250 offset:18432
	ds_read_b128 v[210:213], v160 offset:20480
	ds_read_b128 v[214:217], v250 offset:20480
	ds_read_b128 v[218:221], v160 offset:22528
	ds_read_b128 v[222:225], v250 offset:22528
	global_load_lds_dwordx4 v134, s[6:7]
	s_add_i32 m0, s92, 0x2000
	s_add_u32 s92, s6, 0x41000
	s_addc_u32 s93, s7, 0
	s_add_i32 s94, s83, s67
	global_load_lds_dwordx4 v138, s[6:7]
	s_mov_b32 m0, s94
	s_nop 0
	global_load_lds_dwordx4 v134, s[92:93]
	s_add_i32 m0, s94, 0x2000
	s_nop 0
	global_load_lds_dwordx4 v138, s[92:93]
	s_waitcnt vmcnt(6)
	s_waitcnt lgkmcnt(0)
	s_barrier
	s_setprio 3
	s_waitcnt lgkmcnt(0)
	v_mfma_f32_16x16x32_bf16 v[60:63], v[128:131], v[190:193], v[60:63]
	v_mfma_f32_16x16x32_bf16 v[60:63], v[150:153], v[194:197], v[60:63]
	v_mfma_f32_16x16x32_bf16 v[56:59], v[166:169], v[190:193], v[56:59]
	v_mfma_f32_16x16x32_bf16 v[56:59], v[170:173], v[194:197], v[56:59]
	v_mfma_f32_16x16x32_bf16 v[44:47], v[128:131], v[198:201], v[44:47]
	v_mfma_f32_16x16x32_bf16 v[44:47], v[150:153], v[206:209], v[44:47]
	v_mfma_f32_16x16x32_bf16 v[40:43], v[166:169], v[198:201], v[40:43]
	v_mfma_f32_16x16x32_bf16 v[40:43], v[170:173], v[206:209], v[40:43]
	v_mfma_f32_16x16x32_bf16 v[28:31], v[128:131], v[210:213], v[28:31]
	v_mfma_f32_16x16x32_bf16 v[28:31], v[150:153], v[214:217], v[28:31]
	v_mfma_f32_16x16x32_bf16 v[24:27], v[166:169], v[210:213], v[24:27]
	v_mfma_f32_16x16x32_bf16 v[24:27], v[170:173], v[214:217], v[24:27]
	v_mfma_f32_16x16x32_bf16 v[12:15], v[128:131], v[218:221], v[12:15]
	v_mfma_f32_16x16x32_bf16 v[12:15], v[150:153], v[222:225], v[12:15]
	v_mfma_f32_16x16x32_bf16 v[8:11], v[166:169], v[218:221], v[8:11]
	v_mfma_f32_16x16x32_bf16 v[8:11], v[170:173], v[222:225], v[8:11]
	s_setprio 0
	s_setprio 3
	v_mfma_f32_16x16x32_bf16 v[52:55], v[174:177], v[190:193], v[52:55]
	v_mfma_f32_16x16x32_bf16 v[52:55], v[178:181], v[194:197], v[52:55]
	v_mfma_f32_16x16x32_bf16 v[48:51], v[182:185], v[190:193], v[48:51]
	v_mfma_f32_16x16x32_bf16 v[48:51], v[186:189], v[194:197], v[48:51]
	v_mfma_f32_16x16x32_bf16 v[36:39], v[174:177], v[198:201], v[36:39]
	v_mfma_f32_16x16x32_bf16 v[36:39], v[178:181], v[206:209], v[36:39]
	v_mfma_f32_16x16x32_bf16 v[32:35], v[182:185], v[198:201], v[32:35]
	v_mfma_f32_16x16x32_bf16 v[32:35], v[186:189], v[206:209], v[32:35]
	v_mfma_f32_16x16x32_bf16 v[20:23], v[174:177], v[210:213], v[20:23]
	v_mfma_f32_16x16x32_bf16 v[20:23], v[178:181], v[214:217], v[20:23]
	v_mfma_f32_16x16x32_bf16 v[16:19], v[182:185], v[210:213], v[16:19]
	v_mfma_f32_16x16x32_bf16 v[16:19], v[186:189], v[214:217], v[16:19]
	v_mfma_f32_16x16x32_bf16 v[4:7], v[174:177], v[218:221], v[4:7]
	v_mfma_f32_16x16x32_bf16 v[4:7], v[178:181], v[222:225], v[4:7]
	v_mfma_f32_16x16x32_bf16 v[0:3], v[182:185], v[218:221], v[0:3]
	v_mfma_f32_16x16x32_bf16 v[0:3], v[186:189], v[222:225], v[0:3]
	s_setprio 0
	s_barrier
; #define PG8_STAGE(bufoff, gbase, voff) do { _Pragma("unroll") for (int _i = 0; _i < 2; ++_i) \
;         __builtin_amdgcn_global_load_lds((const unsigned*)((const char*)(gbase) + (voff)[_i]), (LAS unsigned*)(lds + (bufoff) + ldsw + _i * 8192), 16, 0, 0); } while (0)
; #define PG8_LDA(dst, b, h) do { _Pragma("unroll") for (int m = 0; m < 4; ++m) _Pragma("unroll") for (int k = 0; k < 2; ++k) dst[m][k] = *(const LAS bf16x8*)(lds + PG8_SA(b, h) + aoff + m * 2048 + k * 1024); } while (0)
; #define PG8_LDB(dst, b, h) do { _Pragma("unroll") for (int n = 0; n < 2; ++n) _Pragma("unroll") for (int k = 0; k < 2; ++k) dst[n][k] = *(const LAS bf16x8*)(lds + PG8_SB(b, h) + boff + n * 2048 + k * 1024); } while (0)
; #define PG8_MMA(ai, bj, At, Bt) do { __builtin_amdgcn_s_setprio(3); _Pragma("unroll") for (int m = 0; m < 4; ++m) _Pragma("unroll") for (int n = 0; n < 2; ++n) _Pragma("unroll") for (int k = 0; k < 2; ++k) \
;         acc[ai][bj][m][n] = __builtin_amdgcn_mfma_f32_16x16x32_bf16(Bt[n][k], At[m][k], acc[ai][bj][m][n], 0, 0, 0); __builtin_amdgcn_s_setprio(0); } while (0)
; #define PG8_WAIT_V(n) asm volatile("s_waitcnt vmcnt(" #n ")" ::: "memory")
; #define PG8_WAIT_L(n) asm volatile("s_waitcnt lgkmcnt(" #n ")" ::: "memory")
; #define PG8_BAR __builtin_amdgcn_s_barrier()
; #define PG8_SCHED __builtin_amdgcn_sched_barrier(0)
; template <class Epi, class Sched, bool ALIGN_EPI = false, bool SP2 = false>
; __device__ __forceinline__ void gemm_phase(LAS unsigned char* lds, const Gemm g, const Sched& S, const Epi& E) {
;     ...
;             PG8_WAIT_V(8); PG8_WAIT_L(0); PG8_BAR; PG8_MMA(1, 0, At, B0); PG8_MMA(1, 1, At, B1); PG8_BAR; PG8_SCHED;
;             PG8_LDB(B0, 1, 0); PG8_LDB(B1, 1, 1); PG8_SCHED; PG8_LDA(At, 1, 0); PG8_STAGE(PG8_SA(0, 1), a2 + hsA, voffA);
;             PG8_WAIT_V(8); PG8_WAIT_L(0); PG8_BAR; PG8_MMA(0, 0, At, B0); PG8_MMA(0, 1, At, B1); PG8_BAR; PG8_SCHED;
;             PG8_LDA(At, 1, 1); PG8_STAGE(PG8_SB(1, 0), b3, voffB); PG8_STAGE(PG8_SB(1, 1), b3 + hsB, voffB); PG8_STAGE(PG8_SA(1, 0), a3, voffA);
;             PG8_WAIT_V(8); PG8_WAIT_L(0); PG8_BAR; PG8_MMA(1, 0, At, B0); PG8_MMA(1, 1, At, B1); PG8_BAR; PG8_SCHED;
	s_add_i32 s92, 0, 0x18000
	v_add_u32_e32 v165, s92, v156
	v_xor_b32_e32 v253, 64, v165
	s_add_i32 s93, 0, 0x1c000
	ds_read_b128 v[128:131], v165
	ds_read_b128 v[150:153], v253
	ds_read_b128 v[166:169], v165 offset:2048
	ds_read_b128 v[170:173], v253 offset:2048
	v_add_u32_e32 v165, s93, v156
	v_xor_b32_e32 v253, 64, v165
	ds_read_b128 v[174:177], v165
	ds_read_b128 v[178:181], v253
	ds_read_b128 v[182:185], v165 offset:2048
	ds_read_b128 v[186:189], v253 offset:2048
	s_mov_b32 m0, s68
	s_nop 0
	global_load_lds_dwordx4 v132, s[62:63]
	s_mov_b32 m0, s69
	s_nop 0
	global_load_lds_dwordx4 v136, s[62:63]
	s_add_u32 s62, s62, 0x104000
	s_addc_u32 s63, s63, 0
	s_mov_b32 m0, s70
	ds_read_b128 v[190:193], v160 offset:32768
	ds_read_b128 v[194:197], v250 offset:32768
	ds_read_b128 v[198:201], v160 offset:34816
	ds_read_b128 v[206:209], v250 offset:34816
	ds_read_b128 v[210:213], v160 offset:36864
	ds_read_b128 v[214:217], v250 offset:36864
	ds_read_b128 v[218:221], v160 offset:38912
	ds_read_b128 v[222:225], v250 offset:38912
	global_load_lds_dwordx4 v132, s[62:63]
	s_mov_b32 m0, s71
	s_nop 0
	global_load_lds_dwordx4 v136, s[62:63]
	s_waitcnt vmcnt(8)
	s_waitcnt lgkmcnt(0)
	s_barrier
	s_setprio 3
	s_waitcnt lgkmcnt(0)
	v_mfma_f32_16x16x32_bf16 v[124:127], v[128:131], v[190:193], v[124:127]
	v_mfma_f32_16x16x32_bf16 v[124:127], v[150:153], v[194:197], v[124:127]
	v_mfma_f32_16x16x32_bf16 v[120:123], v[166:169], v[190:193], v[120:123]
	v_mfma_f32_16x16x32_bf16 v[120:123], v[170:173], v[194:197], v[120:123]
	v_mfma_f32_16x16x32_bf16 v[108:111], v[128:131], v[198:201], v[108:111]
	v_mfma_f32_16x16x32_bf16 v[108:111], v[150:153], v[206:209], v[108:111]
	v_mfma_f32_16x16x32_bf16 v[104:107], v[166:169], v[198:201], v[104:107]
	v_mfma_f32_16x16x32_bf16 v[104:107], v[170:173], v[206:209], v[104:107]
	v_mfma_f32_16x16x32_bf16 v[92:95], v[128:131], v[210:213], v[92:95]
	v_mfma_f32_16x16x32_bf16 v[92:95], v[150:153], v[214:217], v[92:95]
	v_mfma_f32_16x16x32_bf16 v[88:91], v[166:169], v[210:213], v[88:91]
	v_mfma_f32_16x16x32_bf16 v[88:91], v[170:173], v[214:217], v[88:91]
	v_mfma_f32_16x16x32_bf16 v[76:79], v[128:131], v[218:221], v[76:79]
	v_mfma_f32_16x16x32_bf16 v[76:79], v[150:153], v[222:225], v[76:79]
	v_mfma_f32_16x16x32_bf16 v[72:75], v[166:169], v[218:221], v[72:75]
	v_mfma_f32_16x16x32_bf16 v[72:75], v[170:173], v[222:225], v[72:75]
	s_setprio 0
	s_setprio 3
	v_mfma_f32_16x16x32_bf16 v[116:119], v[174:177], v[190:193], v[116:119]
	v_mfma_f32_16x16x32_bf16 v[116:119], v[178:181], v[194:197], v[116:119]
	v_mfma_f32_16x16x32_bf16 v[112:115], v[182:185], v[190:193], v[112:115]
	v_mfma_f32_16x16x32_bf16 v[112:115], v[186:189], v[194:197], v[112:115]
	v_mfma_f32_16x16x32_bf16 v[100:103], v[174:177], v[198:201], v[100:103]
	v_mfma_f32_16x16x32_bf16 v[100:103], v[178:181], v[206:209], v[100:103]
	v_mfma_f32_16x16x32_bf16 v[96:99], v[182:185], v[198:201], v[96:99]
	v_mfma_f32_16x16x32_bf16 v[96:99], v[186:189], v[206:209], v[96:99]
	v_mfma_f32_16x16x32_bf16 v[84:87], v[174:177], v[210:213], v[84:87]
	v_mfma_f32_16x16x32_bf16 v[84:87], v[178:181], v[214:217], v[84:87]
	v_mfma_f32_16x16x32_bf16 v[80:83], v[182:185], v[210:213], v[80:83]
	v_mfma_f32_16x16x32_bf16 v[80:83], v[186:189], v[214:217], v[80:83]
	v_mfma_f32_16x16x32_bf16 v[68:71], v[174:177], v[218:221], v[68:71]
	v_mfma_f32_16x16x32_bf16 v[68:71], v[178:181], v[222:225], v[68:71]
	v_mfma_f32_16x16x32_bf16 v[64:67], v[182:185], v[218:221], v[64:67]
	v_mfma_f32_16x16x32_bf16 v[64:67], v[186:189], v[222:225], v[64:67]
	s_setprio 0
	s_barrier
	s_add_i32 s62, s92, s67
	s_add_u32 s100, s6, s46
	s_addc_u32 s101, s7, s47
	s_mov_b32 m0, s62
	ds_read_b128 v[190:193], v160 offset:49152
	ds_read_b128 v[194:197], v250 offset:49152
	ds_read_b128 v[198:201], v160 offset:51200
	ds_read_b128 v[206:209], v250 offset:51200
	ds_read_b128 v[210:213], v160 offset:53248
	ds_read_b128 v[214:217], v250 offset:53248
	ds_read_b128 v[218:221], v160 offset:55296
	ds_read_b128 v[222:225], v250 offset:55296
	global_load_lds_dwordx4 v134, s[100:101]
	s_add_i32 m0, s62, 0x2000
	s_add_u32 s6, s6, 0x41080
	s_addc_u32 s7, s7, 0
	s_add_i32 s62, s93, s67
	global_load_lds_dwordx4 v138, s[100:101]
	s_mov_b32 m0, s62
	s_nop 0
	global_load_lds_dwordx4 v134, s[6:7]
	s_add_i32 m0, s62, 0x2000
	s_nop 0
	global_load_lds_dwordx4 v138, s[6:7]
	s_waitcnt vmcnt(6)
	s_waitcnt lgkmcnt(0)
	s_barrier
	s_setprio 3
	s_waitcnt lgkmcnt(0)
	v_mfma_f32_16x16x32_bf16 v[60:63], v[128:131], v[190:193], v[60:63]
	v_mfma_f32_16x16x32_bf16 v[60:63], v[150:153], v[194:197], v[60:63]
	v_mfma_f32_16x16x32_bf16 v[56:59], v[166:169], v[190:193], v[56:59]
	v_mfma_f32_16x16x32_bf16 v[56:59], v[170:173], v[194:197], v[56:59]
	v_mfma_f32_16x16x32_bf16 v[44:47], v[128:131], v[198:201], v[44:47]
	v_mfma_f32_16x16x32_bf16 v[44:47], v[150:153], v[206:209], v[44:47]
	v_mfma_f32_16x16x32_bf16 v[40:43], v[166:169], v[198:201], v[40:43]
	v_mfma_f32_16x16x32_bf16 v[40:43], v[170:173], v[206:209], v[40:43]
	v_mfma_f32_16x16x32_bf16 v[28:31], v[128:131], v[210:213], v[28:31]
	v_mfma_f32_16x16x32_bf16 v[28:31], v[150:153], v[214:217], v[28:31]
	v_mfma_f32_16x16x32_bf16 v[24:27], v[166:169], v[210:213], v[24:27]
	v_mfma_f32_16x16x32_bf16 v[24:27], v[170:173], v[214:217], v[24:27]
	v_mfma_f32_16x16x32_bf16 v[12:15], v[128:131], v[218:221], v[12:15]
	v_mfma_f32_16x16x32_bf16 v[12:15], v[150:153], v[222:225], v[12:15]
	v_mfma_f32_16x16x32_bf16 v[8:11], v[166:169], v[218:221], v[8:11]
	v_mfma_f32_16x16x32_bf16 v[8:11], v[170:173], v[222:225], v[8:11]
	s_setprio 0
	s_setprio 3
	v_mfma_f32_16x16x32_bf16 v[52:55], v[174:177], v[190:193], v[52:55]
	v_mfma_f32_16x16x32_bf16 v[52:55], v[178:181], v[194:197], v[52:55]
	v_mfma_f32_16x16x32_bf16 v[48:51], v[182:185], v[190:193], v[48:51]
	v_mfma_f32_16x16x32_bf16 v[48:51], v[186:189], v[194:197], v[48:51]
	v_mfma_f32_16x16x32_bf16 v[36:39], v[174:177], v[198:201], v[36:39]
	v_mfma_f32_16x16x32_bf16 v[36:39], v[178:181], v[206:209], v[36:39]
	v_mfma_f32_16x16x32_bf16 v[32:35], v[182:185], v[198:201], v[32:35]
	v_mfma_f32_16x16x32_bf16 v[32:35], v[186:189], v[206:209], v[32:35]
	v_mfma_f32_16x16x32_bf16 v[20:23], v[174:177], v[210:213], v[20:23]
	v_mfma_f32_16x16x32_bf16 v[20:23], v[178:181], v[214:217], v[20:23]
	v_mfma_f32_16x16x32_bf16 v[16:19], v[182:185], v[210:213], v[16:19]
	v_mfma_f32_16x16x32_bf16 v[16:19], v[186:189], v[214:217], v[16:19]
	v_mfma_f32_16x16x32_bf16 v[4:7], v[174:177], v[218:221], v[4:7]
	v_mfma_f32_16x16x32_bf16 v[4:7], v[178:181], v[222:225], v[4:7]
	v_mfma_f32_16x16x32_bf16 v[0:3], v[182:185], v[218:221], v[0:3]
	v_mfma_f32_16x16x32_bf16 v[0:3], v[186:189], v[222:225], v[0:3]
	s_setprio 0
	s_barrier
	s_add_i32 s91, s91, 2
	s_add_u32 s4, s4, 0x100
	s_addc_u32 s5, s5, 0
	s_add_u32 s89, s89, 0x100
	s_addc_u32 s90, s90, 0
	s_cmp_gt_u32 s91, 61
	s_cbranch_scc0 .LBB0_64
	s_and_b64 vcc, exec, s[50:51]
	s_cbranch_vccz .LBB0_67
	s_barrier

; #define PG8_STAGE(bufoff, gbase, voff) do { _Pragma("unroll") for (int _i = 0; _i < 2; ++_i) \
;         __builtin_amdgcn_global_load_lds((const unsigned*)((const char*)(gbase) + (voff)[_i]), (LAS unsigned*)(lds + (bufoff) + ldsw + _i * 8192), 16, 0, 0); } while (0)
; #define PG8_LDA(dst, b, h) do { _Pragma("unroll") for (int m = 0; m < 4; ++m) _Pragma("unroll") for (int k = 0; k < 2; ++k) dst[m][k] = *(const LAS bf16x8*)(lds + PG8_SA(b, h) + aoff + m * 2048 + k * 1024); } while (0)
; #define PG8_LDB(dst, b, h) do { _Pragma("unroll") for (int n = 0; n < 2; ++n) _Pragma("unroll") for (int k = 0; k < 2; ++k) dst[n][k] = *(const LAS bf16x8*)(lds + PG8_SB(b, h) + boff + n * 2048 + k * 1024); } while (0)
; #define PG8_MMA(ai, bj, At, Bt) do { __builtin_amdgcn_s_setprio(3); _Pragma("unroll") for (int m = 0; m < 4; ++m) _Pragma("unroll") for (int n = 0; n < 2; ++n) _Pragma("unroll") for (int k = 0; k < 2; ++k) \
;         acc[ai][bj][m][n] = __builtin_amdgcn_mfma_f32_16x16x32_bf16(Bt[n][k], At[m][k], acc[ai][bj][m][n], 0, 0, 0); __builtin_amdgcn_s_setprio(0); } while (0)
; #define PG8_WAIT_V(n) asm volatile("s_waitcnt vmcnt(" #n ")" ::: "memory")
; #define PG8_WAIT_L(n) asm volatile("s_waitcnt lgkmcnt(" #n ")" ::: "memory")
; #define PG8_BAR __builtin_amdgcn_s_barrier()
; #define PG8_SCHED __builtin_amdgcn_sched_barrier(0)
; template <class Epi, class Sched, bool ALIGN_EPI = false, bool SP2 = false>
; __device__ __forceinline__ void gemm_phase(LAS unsigned char* lds, const Gemm g, const Sched& S, const Epi& E) {
;     ...
;             PG8_LDB(B0, 0, 0); PG8_LDB(B1, 0, 1); PG8_SCHED; PG8_LDA(At, 0, 0); PG8_STAGE(PG8_SA(1, 1), a1 + hsA, voffA);
;             PG8_WAIT_V(8); PG8_WAIT_L(0); PG8_BAR; PG8_MMA(0, 0, At, B0); PG8_MMA(0, 1, At, B1); PG8_BAR; PG8_SCHED;
;             PG8_LDA(At, 0, 1); PG8_STAGE(PG8_SB(0, 0), b2, voffB); PG8_STAGE(PG8_SB(0, 1), b2 + hsB, voffB); PG8_STAGE(PG8_SA(0, 0), a2, voffA);
;             PG8_WAIT_V(8); PG8_WAIT_L(0); PG8_BAR; PG8_MMA(1, 0, At, B0); PG8_MMA(1, 1, At, B1); PG8_BAR; PG8_SCHED;
.LBB0_234:
	v_add_u32_e32 v1, s88, v194
	v_xor_b32_e32 v253, 64, v1
	ds_read_b128 v[84:87], v1
	ds_read_b128 v[96:99], v253
	ds_read_b128 v[140:143], v1 offset:2048
	ds_read_b128 v[144:147], v253 offset:2048
	v_add_u32_e32 v1, s89, v194
	v_xor_b32_e32 v253, 64, v1
	s_add_u32 s4, s64, s66
	ds_read_b128 v[152:155], v1
	ds_read_b128 v[156:159], v253
	ds_read_b128 v[160:163], v1 offset:2048
	ds_read_b128 v[182:185], v253 offset:2048
	s_addc_u32 s5, s65, s67
	s_add_u32 s4, s4, 0x100
	s_addc_u32 s5, s5, 0
	s_add_u32 s96, s93, s66
	s_addc_u32 s97, s94, s67
	s_cmpk_eq_i32 s66, 0x1f00
	s_cselect_b32 s9, s59, s5
	s_cselect_b32 s8, s91, s4
	s_cselect_b32 s5, s61, s97
	s_cselect_b32 s4, s60, s96
	s_sub_u32 s100, s66, 0x100000
	s_subb_u32 s101, s67, 0
	v_lshl_add_u64 v[242:243], v[148:149], 0, s[100:101]
	s_mov_b32 m0, s81
	v_lshl_add_u64 v[244:245], v[150:151], 0, s[100:101]
	global_load_lds_dwordx4 v[242:243], off
	s_mov_b32 m0, s82
	s_nop 0
	global_load_lds_dwordx4 v[244:245], off
	v_lshl_add_u64 v[2:3], v[148:149], 0, s[66:67]
	s_add_i32 m0, s41, 0xc000
	ds_read_b128 v[186:189], v198
	ds_read_b128 v[208:211], v250
	ds_read_b128 v[212:215], v198 offset:2048
	ds_read_b128 v[216:219], v250 offset:2048
	ds_read_b128 v[220:223], v198 offset:4096
	ds_read_b128 v[224:227], v250 offset:4096
	ds_read_b128 v[228:231], v198 offset:6144
	ds_read_b128 v[232:235], v250 offset:6144
	global_load_lds_dwordx4 v[2:3], off
	v_lshl_add_u64 v[2:3], v[150:151], 0, s[66:67]
	s_add_i32 m0, s41, 0xe000
	s_nop 0
	global_load_lds_dwordx4 v[2:3], off
	s_waitcnt vmcnt(8)
	s_waitcnt lgkmcnt(0)
	s_barrier
	s_setprio 3
	s_waitcnt lgkmcnt(0)
	v_mfma_f32_16x16x32_bf16 v[136:139], v[84:87], v[186:189], v[136:139]
	v_mfma_f32_16x16x32_bf16 v[136:139], v[96:99], v[208:211], v[136:139]
	v_mfma_f32_16x16x32_bf16 v[132:135], v[140:143], v[186:189], v[132:135]
	v_mfma_f32_16x16x32_bf16 v[132:135], v[144:147], v[208:211], v[132:135]
	v_mfma_f32_16x16x32_bf16 v[120:123], v[84:87], v[212:215], v[120:123]
	v_mfma_f32_16x16x32_bf16 v[120:123], v[96:99], v[216:219], v[120:123]
	v_mfma_f32_16x16x32_bf16 v[116:119], v[140:143], v[212:215], v[116:119]
	v_mfma_f32_16x16x32_bf16 v[116:119], v[144:147], v[216:219], v[116:119]
	v_mfma_f32_16x16x32_bf16 v[104:107], v[84:87], v[220:223], v[104:107]
	v_mfma_f32_16x16x32_bf16 v[104:107], v[96:99], v[224:227], v[104:107]
	v_mfma_f32_16x16x32_bf16 v[100:103], v[140:143], v[220:223], v[100:103]
	v_mfma_f32_16x16x32_bf16 v[100:103], v[144:147], v[224:227], v[100:103]
	v_mfma_f32_16x16x32_bf16 v[80:83], v[84:87], v[228:231], v[80:83]
	v_mfma_f32_16x16x32_bf16 v[80:83], v[96:99], v[232:235], v[80:83]
	v_mfma_f32_16x16x32_bf16 v[76:79], v[140:143], v[228:231], v[76:79]
	v_mfma_f32_16x16x32_bf16 v[76:79], v[144:147], v[232:235], v[76:79]
	s_setprio 0
	s_setprio 3
	v_mfma_f32_16x16x32_bf16 v[128:131], v[152:155], v[186:189], v[128:131]
	v_mfma_f32_16x16x32_bf16 v[128:131], v[156:159], v[208:211], v[128:131]
	v_mfma_f32_16x16x32_bf16 v[124:127], v[160:163], v[186:189], v[124:127]
	v_mfma_f32_16x16x32_bf16 v[124:127], v[182:185], v[208:211], v[124:127]
	v_mfma_f32_16x16x32_bf16 v[112:115], v[152:155], v[212:215], v[112:115]
	v_mfma_f32_16x16x32_bf16 v[112:115], v[156:159], v[216:219], v[112:115]
	v_mfma_f32_16x16x32_bf16 v[108:111], v[160:163], v[212:215], v[108:111]
	v_mfma_f32_16x16x32_bf16 v[108:111], v[182:185], v[216:219], v[108:111]
	v_mfma_f32_16x16x32_bf16 v[92:95], v[152:155], v[220:223], v[92:95]
	v_mfma_f32_16x16x32_bf16 v[92:95], v[156:159], v[224:227], v[92:95]
	v_mfma_f32_16x16x32_bf16 v[88:91], v[160:163], v[220:223], v[88:91]
	v_mfma_f32_16x16x32_bf16 v[88:91], v[182:185], v[224:227], v[88:91]
	v_mfma_f32_16x16x32_bf16 v[72:75], v[152:155], v[228:231], v[72:75]
	v_mfma_f32_16x16x32_bf16 v[72:75], v[156:159], v[232:235], v[72:75]
	v_mfma_f32_16x16x32_bf16 v[68:71], v[160:163], v[228:231], v[68:71]
	v_mfma_f32_16x16x32_bf16 v[68:71], v[182:185], v[232:235], v[68:71]
	s_setprio 0
	s_barrier
	s_add_i32 s96, s88, s31
	s_mov_b32 m0, s96
	ds_read_b128 v[186:189], v198 offset:16384
	ds_read_b128 v[208:211], v250 offset:16384
	ds_read_b128 v[212:215], v198 offset:18432
	ds_read_b128 v[216:219], v250 offset:18432
	ds_read_b128 v[220:223], v198 offset:20480
	ds_read_b128 v[224:227], v250 offset:20480
	ds_read_b128 v[228:231], v198 offset:22528
	ds_read_b128 v[232:235], v250 offset:22528
	global_load_lds_dwordx4 v166, s[4:5]
	s_add_i32 m0, s96, 0x2000
	s_add_u32 s96, s4, 0x104000
	s_addc_u32 s97, s5, 0
	s_add_i32 s98, s89, s31
	global_load_lds_dwordx4 v170, s[4:5]
	s_mov_b32 m0, s98
	s_nop 0
	global_load_lds_dwordx4 v166, s[96:97]
	s_add_i32 m0, s98, 0x2000
	s_nop 0
	global_load_lds_dwordx4 v170, s[96:97]
	s_waitcnt vmcnt(6)
	s_waitcnt lgkmcnt(0)
	s_barrier
; #define PG8_STAGE(bufoff, gbase, voff) do { _Pragma("unroll") for (int _i = 0; _i < 2; ++_i) \
;         __builtin_amdgcn_global_load_lds((const unsigned*)((const char*)(gbase) + (voff)[_i]), (LAS unsigned*)(lds + (bufoff) + ldsw + _i * 8192), 16, 0, 0); } while (0)
; #define PG8_LDA(dst, b, h) do { _Pragma("unroll") for (int m = 0; m < 4; ++m) _Pragma("unroll") for (int k = 0; k < 2; ++k) dst[m][k] = *(const LAS bf16x8*)(lds + PG8_SA(b, h) + aoff + m * 2048 + k * 1024); } while (0)
; #define PG8_LDB(dst, b, h) do { _Pragma("unroll") for (int n = 0; n < 2; ++n) _Pragma("unroll") for (int k = 0; k < 2; ++k) dst[n][k] = *(const LAS bf16x8*)(lds + PG8_SB(b, h) + boff + n * 2048 + k * 1024); } while (0)
; #define PG8_MMA(ai, bj, At, Bt) do { __builtin_amdgcn_s_setprio(3); _Pragma("unroll") for (int m = 0; m < 4; ++m) _Pragma("unroll") for (int n = 0; n < 2; ++n) _Pragma("unroll") for (int k = 0; k < 2; ++k) \
;         acc[ai][bj][m][n] = __builtin_amdgcn_mfma_f32_16x16x32_bf16(Bt[n][k], At[m][k], acc[ai][bj][m][n], 0, 0, 0); __builtin_amdgcn_s_setprio(0); } while (0)
; #define PG8_WAIT_V(n) asm volatile("s_waitcnt vmcnt(" #n ")" ::: "memory")
; #define PG8_WAIT_L(n) asm volatile("s_waitcnt lgkmcnt(" #n ")" ::: "memory")
; #define PG8_BAR __builtin_amdgcn_s_barrier()
; #define PG8_SCHED __builtin_amdgcn_sched_barrier(0)
; template <class Epi, class Sched, bool ALIGN_EPI = false, bool SP2 = false>
; __device__ __forceinline__ void gemm_phase(LAS unsigned char* lds, const Gemm g, const Sched& S, const Epi& E) {
;     ...
;             PG8_WAIT_V(8); PG8_WAIT_L(0); PG8_BAR; PG8_MMA(1, 0, At, B0); PG8_MMA(1, 1, At, B1); PG8_BAR; PG8_SCHED;
;             PG8_LDB(B0, 1, 0); PG8_LDB(B1, 1, 1); PG8_SCHED; PG8_LDA(At, 1, 0); PG8_STAGE(PG8_SA(0, 1), a2 + hsA, voffA);
;             PG8_WAIT_V(8); PG8_WAIT_L(0); PG8_BAR; PG8_MMA(0, 0, At, B0); PG8_MMA(0, 1, At, B1); PG8_BAR; PG8_SCHED;
	s_setprio 3
	s_waitcnt lgkmcnt(0)
	v_mfma_f32_16x16x32_bf16 v[64:67], v[84:87], v[186:189], v[64:67]
	v_mfma_f32_16x16x32_bf16 v[64:67], v[96:99], v[208:211], v[64:67]
	v_mfma_f32_16x16x32_bf16 v[60:63], v[140:143], v[186:189], v[60:63]
	v_mfma_f32_16x16x32_bf16 v[60:63], v[144:147], v[208:211], v[60:63]
	v_mfma_f32_16x16x32_bf16 v[48:51], v[84:87], v[212:215], v[48:51]
	v_mfma_f32_16x16x32_bf16 v[48:51], v[96:99], v[216:219], v[48:51]
	v_mfma_f32_16x16x32_bf16 v[44:47], v[140:143], v[212:215], v[44:47]
	v_mfma_f32_16x16x32_bf16 v[44:47], v[144:147], v[216:219], v[44:47]
	v_mfma_f32_16x16x32_bf16 v[32:35], v[84:87], v[220:223], v[32:35]
	v_mfma_f32_16x16x32_bf16 v[32:35], v[96:99], v[224:227], v[32:35]
	v_mfma_f32_16x16x32_bf16 v[28:31], v[140:143], v[220:223], v[28:31]
	v_mfma_f32_16x16x32_bf16 v[28:31], v[144:147], v[224:227], v[28:31]
	v_mfma_f32_16x16x32_bf16 v[16:19], v[84:87], v[228:231], v[16:19]
	v_mfma_f32_16x16x32_bf16 v[16:19], v[96:99], v[232:235], v[16:19]
	v_mfma_f32_16x16x32_bf16 v[12:15], v[140:143], v[228:231], v[12:15]
	v_mfma_f32_16x16x32_bf16 v[12:15], v[144:147], v[232:235], v[12:15]
	s_setprio 0
	s_setprio 3
	v_mfma_f32_16x16x32_bf16 v[56:59], v[152:155], v[186:189], v[56:59]
	v_mfma_f32_16x16x32_bf16 v[56:59], v[156:159], v[208:211], v[56:59]
	v_mfma_f32_16x16x32_bf16 v[52:55], v[160:163], v[186:189], v[52:55]
	v_mfma_f32_16x16x32_bf16 v[52:55], v[182:185], v[208:211], v[52:55]
	v_mfma_f32_16x16x32_bf16 v[40:43], v[152:155], v[212:215], v[40:43]
	v_mfma_f32_16x16x32_bf16 v[40:43], v[156:159], v[216:219], v[40:43]
	v_mfma_f32_16x16x32_bf16 v[36:39], v[160:163], v[212:215], v[36:39]
	v_mfma_f32_16x16x32_bf16 v[36:39], v[182:185], v[216:219], v[36:39]
	v_mfma_f32_16x16x32_bf16 v[24:27], v[152:155], v[220:223], v[24:27]
	v_mfma_f32_16x16x32_bf16 v[24:27], v[156:159], v[224:227], v[24:27]
	v_mfma_f32_16x16x32_bf16 v[20:23], v[160:163], v[220:223], v[20:23]
	v_mfma_f32_16x16x32_bf16 v[20:23], v[182:185], v[224:227], v[20:23]
	v_mfma_f32_16x16x32_bf16 v[8:11], v[152:155], v[228:231], v[8:11]
	v_mfma_f32_16x16x32_bf16 v[8:11], v[156:159], v[232:235], v[8:11]
	v_mfma_f32_16x16x32_bf16 v[2:5], v[160:163], v[228:231], v[4:7]
	v_mfma_f32_16x16x32_bf16 v[2:5], v[182:185], v[232:235], v[2:5]
	s_setprio 0
	s_barrier
	s_add_i32 s96, 0, 0x18000
	v_add_u32_e32 v1, s96, v194
	v_xor_b32_e32 v253, 64, v1
	s_add_i32 s97, 0, 0x1c000
	ds_read_b128 v[84:87], v1
	ds_read_b128 v[96:99], v253
	ds_read_b128 v[140:143], v1 offset:2048
	ds_read_b128 v[144:147], v253 offset:2048
	v_add_u32_e32 v1, s97, v194
	v_xor_b32_e32 v253, 64, v1
	ds_read_b128 v[152:155], v1
	ds_read_b128 v[156:159], v253
	ds_read_b128 v[160:163], v1 offset:2048
	ds_read_b128 v[182:185], v253 offset:2048
	s_mov_b32 m0, s41
	s_nop 0
	global_load_lds_dwordx4 v164, s[8:9]
	s_mov_b32 m0, s68
	s_nop 0
	global_load_lds_dwordx4 v168, s[8:9]
	s_add_u32 s8, s8, 0x100000
	s_addc_u32 s9, s9, 0
	s_mov_b32 m0, s69
	ds_read_b128 v[186:189], v198 offset:32768
	ds_read_b128 v[208:211], v250 offset:32768
	ds_read_b128 v[212:215], v198 offset:34816
	ds_read_b128 v[216:219], v250 offset:34816
	ds_read_b128 v[220:223], v198 offset:36864
	ds_read_b128 v[224:227], v250 offset:36864
	ds_read_b128 v[228:231], v198 offset:38912
	ds_read_b128 v[232:235], v250 offset:38912
	global_load_lds_dwordx4 v164, s[8:9]
	s_mov_b32 m0, s70
	s_nop 0
	global_load_lds_dwordx4 v168, s[8:9]
	s_waitcnt vmcnt(8)
	s_waitcnt lgkmcnt(0)
	s_barrier
; #define PG8_STAGE(bufoff, gbase, voff) do { _Pragma("unroll") for (int _i = 0; _i < 2; ++_i) \
;         __builtin_amdgcn_global_load_lds((const unsigned*)((const char*)(gbase) + (voff)[_i]), (LAS unsigned*)(lds + (bufoff) + ldsw + _i * 8192), 16, 0, 0); } while (0)
; #define PG8_LDA(dst, b, h) do { _Pragma("unroll") for (int m = 0; m < 4; ++m) _Pragma("unroll") for (int k = 0; k < 2; ++k) dst[m][k] = *(const LAS bf16x8*)(lds + PG8_SA(b, h) + aoff + m * 2048 + k * 1024); } while (0)
; #define PG8_MMA(ai, bj, At, Bt) do { __builtin_amdgcn_s_setprio(3); _Pragma("unroll") for (int m = 0; m < 4; ++m) _Pragma("unroll") for (int n = 0; n < 2; ++n) _Pragma("unroll") for (int k = 0; k < 2; ++k) \
;         acc[ai][bj][m][n] = __builtin_amdgcn_mfma_f32_16x16x32_bf16(Bt[n][k], At[m][k], acc[ai][bj][m][n], 0, 0, 0); __builtin_amdgcn_s_setprio(0); } while (0)
; #define PG8_WAIT_V(n) asm volatile("s_waitcnt vmcnt(" #n ")" ::: "memory")
; #define PG8_WAIT_L(n) asm volatile("s_waitcnt lgkmcnt(" #n ")" ::: "memory")
; #define PG8_BAR __builtin_amdgcn_s_barrier()
; #define PG8_SCHED __builtin_amdgcn_sched_barrier(0)
; template <class Epi, class Sched, bool ALIGN_EPI = false, bool SP2 = false>
; __device__ __forceinline__ void gemm_phase(LAS unsigned char* lds, const Gemm g, const Sched& S, const Epi& E) {
;     ...
;             PG8_WAIT_V(8); PG8_WAIT_L(0); PG8_BAR; PG8_MMA(0, 0, At, B0); PG8_MMA(0, 1, At, B1); PG8_BAR; PG8_SCHED;
;             PG8_LDA(At, 1, 1); PG8_STAGE(PG8_SB(1, 0), b3, voffB); PG8_STAGE(PG8_SB(1, 1), b3 + hsB, voffB); PG8_STAGE(PG8_SA(1, 0), a3, voffA);
;             PG8_WAIT_V(8); PG8_WAIT_L(0); PG8_BAR; PG8_MMA(1, 0, At, B0); PG8_MMA(1, 1, At, B1); PG8_BAR; PG8_SCHED;
	s_setprio 3
	s_waitcnt lgkmcnt(0)
	v_mfma_f32_16x16x32_bf16 v[136:139], v[84:87], v[186:189], v[136:139]
	v_mfma_f32_16x16x32_bf16 v[136:139], v[96:99], v[208:211], v[136:139]
	v_mfma_f32_16x16x32_bf16 v[132:135], v[140:143], v[186:189], v[132:135]
	v_mfma_f32_16x16x32_bf16 v[132:135], v[144:147], v[208:211], v[132:135]
	v_mfma_f32_16x16x32_bf16 v[120:123], v[84:87], v[212:215], v[120:123]
	v_mfma_f32_16x16x32_bf16 v[120:123], v[96:99], v[216:219], v[120:123]
	v_mfma_f32_16x16x32_bf16 v[116:119], v[140:143], v[212:215], v[116:119]
	v_mfma_f32_16x16x32_bf16 v[116:119], v[144:147], v[216:219], v[116:119]
	v_mfma_f32_16x16x32_bf16 v[104:107], v[84:87], v[220:223], v[104:107]
	v_mfma_f32_16x16x32_bf16 v[104:107], v[96:99], v[224:227], v[104:107]
	v_mfma_f32_16x16x32_bf16 v[100:103], v[140:143], v[220:223], v[100:103]
	v_mfma_f32_16x16x32_bf16 v[100:103], v[144:147], v[224:227], v[100:103]
	v_mfma_f32_16x16x32_bf16 v[80:83], v[84:87], v[228:231], v[80:83]
	v_mfma_f32_16x16x32_bf16 v[80:83], v[96:99], v[232:235], v[80:83]
	v_mfma_f32_16x16x32_bf16 v[76:79], v[140:143], v[228:231], v[76:79]
	v_mfma_f32_16x16x32_bf16 v[76:79], v[144:147], v[232:235], v[76:79]
	s_setprio 0
	s_setprio 3
	v_mfma_f32_16x16x32_bf16 v[128:131], v[152:155], v[186:189], v[128:131]
	v_mfma_f32_16x16x32_bf16 v[128:131], v[156:159], v[208:211], v[128:131]
	v_mfma_f32_16x16x32_bf16 v[124:127], v[160:163], v[186:189], v[124:127]
	v_mfma_f32_16x16x32_bf16 v[124:127], v[182:185], v[208:211], v[124:127]
	v_mfma_f32_16x16x32_bf16 v[112:115], v[152:155], v[212:215], v[112:115]
	v_mfma_f32_16x16x32_bf16 v[112:115], v[156:159], v[216:219], v[112:115]
	v_mfma_f32_16x16x32_bf16 v[108:111], v[160:163], v[212:215], v[108:111]
	v_mfma_f32_16x16x32_bf16 v[108:111], v[182:185], v[216:219], v[108:111]
	v_mfma_f32_16x16x32_bf16 v[92:95], v[152:155], v[220:223], v[92:95]
	v_mfma_f32_16x16x32_bf16 v[92:95], v[156:159], v[224:227], v[92:95]
	v_mfma_f32_16x16x32_bf16 v[88:91], v[160:163], v[220:223], v[88:91]
	v_mfma_f32_16x16x32_bf16 v[88:91], v[182:185], v[224:227], v[88:91]
	v_mfma_f32_16x16x32_bf16 v[72:75], v[152:155], v[228:231], v[72:75]
	v_mfma_f32_16x16x32_bf16 v[72:75], v[156:159], v[232:235], v[72:75]
	v_mfma_f32_16x16x32_bf16 v[68:71], v[160:163], v[228:231], v[68:71]
	v_mfma_f32_16x16x32_bf16 v[68:71], v[182:185], v[232:235], v[68:71]
	s_setprio 0
	s_barrier
	s_add_i32 s8, s96, s31
	s_add_u32 s100, s4, s24
	s_addc_u32 s101, s5, s25
	s_mov_b32 m0, s8
	ds_read_b128 v[186:189], v198 offset:49152
	ds_read_b128 v[208:211], v250 offset:49152
	ds_read_b128 v[212:215], v198 offset:51200
	ds_read_b128 v[216:219], v250 offset:51200
	ds_read_b128 v[220:223], v198 offset:53248
	ds_read_b128 v[224:227], v250 offset:53248
	ds_read_b128 v[228:231], v198 offset:55296
	ds_read_b128 v[232:235], v250 offset:55296
	global_load_lds_dwordx4 v166, s[100:101]
	s_add_i32 m0, s8, 0x2000
	s_add_u32 s4, s4, 0x104080
	s_addc_u32 s5, s5, 0
	s_add_i32 s8, s97, s31
	global_load_lds_dwordx4 v170, s[100:101]
	s_mov_b32 m0, s8
	s_nop 0
	global_load_lds_dwordx4 v166, s[4:5]
	s_add_i32 m0, s8, 0x2000
	s_nop 0
	global_load_lds_dwordx4 v170, s[4:5]
	s_waitcnt vmcnt(6)
	s_waitcnt lgkmcnt(0)
	s_barrier
	s_setprio 3
	s_waitcnt lgkmcnt(0)
	v_mfma_f32_16x16x32_bf16 v[64:67], v[84:87], v[186:189], v[64:67]
	v_mfma_f32_16x16x32_bf16 v[64:67], v[96:99], v[208:211], v[64:67]
	v_mfma_f32_16x16x32_bf16 v[60:63], v[140:143], v[186:189], v[60:63]
	v_mfma_f32_16x16x32_bf16 v[60:63], v[144:147], v[208:211], v[60:63]
	v_mfma_f32_16x16x32_bf16 v[48:51], v[84:87], v[212:215], v[48:51]
	v_mfma_f32_16x16x32_bf16 v[48:51], v[96:99], v[216:219], v[48:51]
	v_mfma_f32_16x16x32_bf16 v[44:47], v[140:143], v[212:215], v[44:47]
	v_mfma_f32_16x16x32_bf16 v[44:47], v[144:147], v[216:219], v[44:47]
	v_mfma_f32_16x16x32_bf16 v[32:35], v[84:87], v[220:223], v[32:35]
	v_mfma_f32_16x16x32_bf16 v[32:35], v[96:99], v[224:227], v[32:35]
	v_mfma_f32_16x16x32_bf16 v[28:31], v[140:143], v[220:223], v[28:31]
	v_mfma_f32_16x16x32_bf16 v[28:31], v[144:147], v[224:227], v[28:31]
	v_mfma_f32_16x16x32_bf16 v[16:19], v[84:87], v[228:231], v[16:19]
	v_mfma_f32_16x16x32_bf16 v[16:19], v[96:99], v[232:235], v[16:19]
	v_mfma_f32_16x16x32_bf16 v[12:15], v[140:143], v[228:231], v[12:15]
	v_mfma_f32_16x16x32_bf16 v[12:15], v[144:147], v[232:235], v[12:15]
	s_setprio 0
	s_setprio 3
	v_mfma_f32_16x16x32_bf16 v[56:59], v[152:155], v[186:189], v[56:59]
	v_mfma_f32_16x16x32_bf16 v[56:59], v[156:159], v[208:211], v[56:59]
	v_mfma_f32_16x16x32_bf16 v[52:55], v[160:163], v[186:189], v[52:55]
	v_mfma_f32_16x16x32_bf16 v[52:55], v[182:185], v[208:211], v[52:55]
	v_mfma_f32_16x16x32_bf16 v[40:43], v[152:155], v[212:215], v[40:43]
	v_mfma_f32_16x16x32_bf16 v[40:43], v[156:159], v[216:219], v[40:43]
	v_mfma_f32_16x16x32_bf16 v[36:39], v[160:163], v[212:215], v[36:39]
	v_mfma_f32_16x16x32_bf16 v[36:39], v[182:185], v[216:219], v[36:39]
	v_mfma_f32_16x16x32_bf16 v[24:27], v[152:155], v[220:223], v[24:27]
	v_mfma_f32_16x16x32_bf16 v[24:27], v[156:159], v[224:227], v[24:27]
	v_mfma_f32_16x16x32_bf16 v[20:23], v[160:163], v[220:223], v[20:23]
	v_mfma_f32_16x16x32_bf16 v[20:23], v[182:185], v[224:227], v[20:23]
	v_mfma_f32_16x16x32_bf16 v[6:9], v[152:155], v[228:231], v[8:11]
	v_mfma_f32_16x16x32_bf16 v[8:11], v[156:159], v[232:235], v[6:9]
	v_mfma_f32_16x16x32_bf16 v[2:5], v[160:163], v[228:231], v[2:5]
	v_mfma_f32_16x16x32_bf16 v[4:7], v[182:185], v[232:235], v[2:5]
	s_setprio 0
	s_barrier
	s_add_i32 s95, s95, 2
	s_add_u32 s66, s66, 0x100
	s_addc_u32 s67, s67, 0
	s_cmp_gt_u32 s95, 61
	s_cbranch_scc1 .LBB0_237

; #define PG8_STAGE(bufoff, gbase, voff) do { _Pragma("unroll") for (int _i = 0; _i < 2; ++_i) \
;         __builtin_amdgcn_global_load_lds((const unsigned*)((const char*)(gbase) + (voff)[_i]), (LAS unsigned*)(lds + (bufoff) + ldsw + _i * 8192), 16, 0, 0); } while (0)
; #define PG8_LDA(dst, b, h) do { _Pragma("unroll") for (int m = 0; m < 4; ++m) _Pragma("unroll") for (int k = 0; k < 2; ++k) dst[m][k] = *(const LAS bf16x8*)(lds + PG8_SA(b, h) + aoff + m * 2048 + k * 1024); } while (0)
; #define PG8_LDB(dst, b, h) do { _Pragma("unroll") for (int n = 0; n < 2; ++n) _Pragma("unroll") for (int k = 0; k < 2; ++k) dst[n][k] = *(const LAS bf16x8*)(lds + PG8_SB(b, h) + boff + n * 2048 + k * 1024); } while (0)
; #define PG8_MMA(ai, bj, At, Bt) do { __builtin_amdgcn_s_setprio(3); _Pragma("unroll") for (int m = 0; m < 4; ++m) _Pragma("unroll") for (int n = 0; n < 2; ++n) _Pragma("unroll") for (int k = 0; k < 2; ++k) \
;         acc[ai][bj][m][n] = __builtin_amdgcn_mfma_f32_16x16x32_bf16(Bt[n][k], At[m][k], acc[ai][bj][m][n], 0, 0, 0); __builtin_amdgcn_s_setprio(0); } while (0)
; #define PG8_WAIT_V(n) asm volatile("s_waitcnt vmcnt(" #n ")" ::: "memory")
; #define PG8_WAIT_L(n) asm volatile("s_waitcnt lgkmcnt(" #n ")" ::: "memory")
; #define PG8_BAR __builtin_amdgcn_s_barrier()
; template <class Epi, class Sched, bool ALIGN_EPI = false, bool SP2 = false>
; __device__ __forceinline__ void gemm_phase(LAS unsigned char* lds, const Gemm g, const Sched& S, const Epi& E) {
;     ...
;             const char* a2 = last ? nA : cA + (size_t)(t + 2) * kstep; const char* b2 = last ? nB : cB + (size_t)(t + 2) * kstep;
;             const char* a3 = a2 + kstep; const char* b3 = b2 + kstep;
;             if (last && has_next) S.a_ready(nxt);
;             if constexpr (Epi::MID) { if (t == nt / 2) E.mid(acc, cur, wr, wc, fr, fq); }
;             if constexpr (SP2) {
;             PG8_LDB(B0, 0, 0); PG8_LDB(B1, 0, 1); PG8_SCHED; PG8_LDA(At, 0, 0); PG8_STAGE(PG8_SA(1, 1), a1 + hsA, voffA);
;             PG8_WAIT_V(8); PG8_WAIT_L(0); PG8_BAR; PG8_MMA(0, 0, At, B0); PG8_MMA(0, 1, At, B1); PG8_BAR; PG8_SCHED;
;             PG8_LDA(At, 0, 1); PG8_STAGE(PG8_SB(0, 0), b2, voffB); PG8_STAGE(PG8_SB(0, 1), b2 + hsB, voffB); PG8_STAGE(PG8_SA(0, 0), a2, voffA);
;             PG8_WAIT_V(8); PG8_WAIT_L(0); PG8_BAR; PG8_MMA(1, 0, At, B0); PG8_MMA(1, 1, At, B1); PG8_BAR; PG8_SCHED;
.LBB0_309:
	ds_read_b128 v[112:115], v175
	ds_read_b128 v[132:135], v251
	ds_read_b128 v[136:139], v175 offset:2048
	ds_read_b128 v[140:143], v251 offset:2048
	ds_read_b128 v[144:147], v176
	ds_read_b128 v[148:151], v252
	ds_read_b128 v[184:187], v176 offset:2048
	ds_read_b128 v[188:191], v252 offset:2048
	s_add_u32 s24, s4, 0xffefc080
	s_addc_u32 s25, s5, -1
	s_cmp_eq_u32 s73, 60
	s_cselect_b32 s27, s11, s25
	s_cselect_b32 s26, s10, s24
	s_cselect_b32 s25, s21, s72
	s_cselect_b32 s24, s20, s71
	s_sub_u32 s100, s4, 0x104000
	s_subb_u32 s101, s5, 0
	s_mov_b32 m0, s42
	s_nop 0
	global_load_lds_dwordx4 v152, s[100:101]
	s_mov_b32 m0, s43
	s_nop 0
	global_load_lds_dwordx4 v156, s[100:101]
	s_add_i32 m0, s36, 0xc000
	ds_read_b128 v[192:195], v177
	ds_read_b128 v[196:199], v250
	ds_read_b128 v[206:209], v177 offset:2048
	ds_read_b128 v[210:213], v250 offset:2048
	ds_read_b128 v[214:217], v177 offset:4096
	ds_read_b128 v[218:221], v250 offset:4096
	ds_read_b128 v[222:225], v177 offset:6144
	ds_read_b128 v[226:229], v250 offset:6144
	global_load_lds_dwordx4 v164, s[4:5]
	s_add_i32 m0, s36, 0xe000
	s_nop 0
	global_load_lds_dwordx4 v166, s[4:5]
	s_waitcnt vmcnt(8)
	s_waitcnt lgkmcnt(0)
	s_barrier
	s_setprio 3
	s_waitcnt lgkmcnt(0)
	v_mfma_f32_16x16x32_bf16 v[128:131], v[112:115], v[192:195], v[128:131]
	v_mfma_f32_16x16x32_bf16 v[128:131], v[132:135], v[196:199], v[128:131]
	v_mfma_f32_16x16x32_bf16 v[124:127], v[136:139], v[192:195], v[124:127]
	v_mfma_f32_16x16x32_bf16 v[124:127], v[140:143], v[196:199], v[124:127]
	v_mfma_f32_16x16x32_bf16 v[108:111], v[112:115], v[206:209], v[108:111]
	v_mfma_f32_16x16x32_bf16 v[108:111], v[132:135], v[210:213], v[108:111]
	v_mfma_f32_16x16x32_bf16 v[104:107], v[136:139], v[206:209], v[104:107]
	v_mfma_f32_16x16x32_bf16 v[104:107], v[140:143], v[210:213], v[104:107]
	v_mfma_f32_16x16x32_bf16 v[92:95], v[112:115], v[214:217], v[92:95]
	v_mfma_f32_16x16x32_bf16 v[92:95], v[132:135], v[218:221], v[92:95]
	v_mfma_f32_16x16x32_bf16 v[88:91], v[136:139], v[214:217], v[88:91]
	v_mfma_f32_16x16x32_bf16 v[88:91], v[140:143], v[218:221], v[88:91]
	v_mfma_f32_16x16x32_bf16 v[76:79], v[112:115], v[222:225], v[76:79]
	v_mfma_f32_16x16x32_bf16 v[76:79], v[132:135], v[226:229], v[76:79]
	v_mfma_f32_16x16x32_bf16 v[72:75], v[136:139], v[222:225], v[72:75]
	v_mfma_f32_16x16x32_bf16 v[72:75], v[140:143], v[226:229], v[72:75]
	s_setprio 0
	s_setprio 3
	v_mfma_f32_16x16x32_bf16 v[120:123], v[144:147], v[192:195], v[120:123]
	v_mfma_f32_16x16x32_bf16 v[120:123], v[148:151], v[196:199], v[120:123]
	v_mfma_f32_16x16x32_bf16 v[116:119], v[184:187], v[192:195], v[116:119]
	v_mfma_f32_16x16x32_bf16 v[116:119], v[188:191], v[196:199], v[116:119]
	v_mfma_f32_16x16x32_bf16 v[100:103], v[144:147], v[206:209], v[100:103]
	v_mfma_f32_16x16x32_bf16 v[100:103], v[148:151], v[210:213], v[100:103]
	v_mfma_f32_16x16x32_bf16 v[96:99], v[184:187], v[206:209], v[96:99]
	v_mfma_f32_16x16x32_bf16 v[96:99], v[188:191], v[210:213], v[96:99]
	v_mfma_f32_16x16x32_bf16 v[84:87], v[144:147], v[214:217], v[84:87]
	v_mfma_f32_16x16x32_bf16 v[84:87], v[148:151], v[218:221], v[84:87]
	v_mfma_f32_16x16x32_bf16 v[80:83], v[184:187], v[214:217], v[80:83]
	v_mfma_f32_16x16x32_bf16 v[80:83], v[188:191], v[218:221], v[80:83]
	v_mfma_f32_16x16x32_bf16 v[68:71], v[144:147], v[222:225], v[68:71]
	v_mfma_f32_16x16x32_bf16 v[68:71], v[148:151], v[226:229], v[68:71]
	v_mfma_f32_16x16x32_bf16 v[64:67], v[184:187], v[222:225], v[64:67]
	v_mfma_f32_16x16x32_bf16 v[64:67], v[188:191], v[226:229], v[64:67]
	s_setprio 0
	s_barrier
	s_add_i32 s74, s45, s31
	s_mov_b32 m0, s74
	ds_read_b128 v[192:195], v177 offset:16384
	ds_read_b128 v[196:199], v250 offset:16384
	ds_read_b128 v[206:209], v177 offset:18432
	ds_read_b128 v[210:213], v250 offset:18432
	ds_read_b128 v[214:217], v177 offset:20480
	ds_read_b128 v[218:221], v250 offset:20480
	ds_read_b128 v[222:225], v177 offset:22528
	ds_read_b128 v[226:229], v250 offset:22528
	global_load_lds_dwordx4 v154, s[24:25]
	s_add_i32 m0, s74, 0x2000
	s_add_u32 s74, s24, 0x41000
	s_addc_u32 s75, s25, 0
	s_add_i32 s78, s46, s31
	global_load_lds_dwordx4 v158, s[24:25]
	s_mov_b32 m0, s78
	s_nop 0
	global_load_lds_dwordx4 v154, s[74:75]
	s_add_i32 m0, s78, 0x2000
	s_nop 0
	global_load_lds_dwordx4 v158, s[74:75]
	s_waitcnt vmcnt(6)
	s_waitcnt lgkmcnt(0)
	s_barrier
	s_setprio 3
	s_waitcnt lgkmcnt(0)
	v_mfma_f32_16x16x32_bf16 v[60:63], v[112:115], v[192:195], v[60:63]
	v_mfma_f32_16x16x32_bf16 v[60:63], v[132:135], v[196:199], v[60:63]
	v_mfma_f32_16x16x32_bf16 v[56:59], v[136:139], v[192:195], v[56:59]
	v_mfma_f32_16x16x32_bf16 v[56:59], v[140:143], v[196:199], v[56:59]
	v_mfma_f32_16x16x32_bf16 v[44:47], v[112:115], v[206:209], v[44:47]
	v_mfma_f32_16x16x32_bf16 v[44:47], v[132:135], v[210:213], v[44:47]
	v_mfma_f32_16x16x32_bf16 v[40:43], v[136:139], v[206:209], v[40:43]
	v_mfma_f32_16x16x32_bf16 v[40:43], v[140:143], v[210:213], v[40:43]
	v_mfma_f32_16x16x32_bf16 v[28:31], v[112:115], v[214:217], v[28:31]
	v_mfma_f32_16x16x32_bf16 v[28:31], v[132:135], v[218:221], v[28:31]
	v_mfma_f32_16x16x32_bf16 v[24:27], v[136:139], v[214:217], v[24:27]
	v_mfma_f32_16x16x32_bf16 v[24:27], v[140:143], v[218:221], v[24:27]
	v_mfma_f32_16x16x32_bf16 v[12:15], v[112:115], v[222:225], v[12:15]
	v_mfma_f32_16x16x32_bf16 v[12:15], v[132:135], v[226:229], v[12:15]
	v_mfma_f32_16x16x32_bf16 v[8:11], v[136:139], v[222:225], v[8:11]
	v_mfma_f32_16x16x32_bf16 v[8:11], v[140:143], v[226:229], v[8:11]
	s_setprio 0
	s_setprio 3
	v_mfma_f32_16x16x32_bf16 v[52:55], v[144:147], v[192:195], v[52:55]
	v_mfma_f32_16x16x32_bf16 v[52:55], v[148:151], v[196:199], v[52:55]
	v_mfma_f32_16x16x32_bf16 v[48:51], v[184:187], v[192:195], v[48:51]
	v_mfma_f32_16x16x32_bf16 v[48:51], v[188:191], v[196:199], v[48:51]
	v_mfma_f32_16x16x32_bf16 v[36:39], v[144:147], v[206:209], v[36:39]
	v_mfma_f32_16x16x32_bf16 v[36:39], v[148:151], v[210:213], v[36:39]
	v_mfma_f32_16x16x32_bf16 v[32:35], v[184:187], v[206:209], v[32:35]
	v_mfma_f32_16x16x32_bf16 v[32:35], v[188:191], v[210:213], v[32:35]
	v_mfma_f32_16x16x32_bf16 v[20:23], v[144:147], v[214:217], v[20:23]
	v_mfma_f32_16x16x32_bf16 v[20:23], v[148:151], v[218:221], v[20:23]
	v_mfma_f32_16x16x32_bf16 v[16:19], v[184:187], v[214:217], v[16:19]
	v_mfma_f32_16x16x32_bf16 v[16:19], v[188:191], v[218:221], v[16:19]
	v_mfma_f32_16x16x32_bf16 v[4:7], v[144:147], v[222:225], v[4:7]
	v_mfma_f32_16x16x32_bf16 v[4:7], v[148:151], v[226:229], v[4:7]
	v_mfma_f32_16x16x32_bf16 v[0:3], v[184:187], v[222:225], v[0:3]
	v_mfma_f32_16x16x32_bf16 v[0:3], v[188:191], v[226:229], v[0:3]
	s_setprio 0
	s_barrier
; #define PG8_STAGE(bufoff, gbase, voff) do { _Pragma("unroll") for (int _i = 0; _i < 2; ++_i) \
;         __builtin_amdgcn_global_load_lds((const unsigned*)((const char*)(gbase) + (voff)[_i]), (LAS unsigned*)(lds + (bufoff) + ldsw + _i * 8192), 16, 0, 0); } while (0)
; #define PG8_LDA(dst, b, h) do { _Pragma("unroll") for (int m = 0; m < 4; ++m) _Pragma("unroll") for (int k = 0; k < 2; ++k) dst[m][k] = *(const LAS bf16x8*)(lds + PG8_SA(b, h) + aoff + m * 2048 + k * 1024); } while (0)
; #define PG8_LDB(dst, b, h) do { _Pragma("unroll") for (int n = 0; n < 2; ++n) _Pragma("unroll") for (int k = 0; k < 2; ++k) dst[n][k] = *(const LAS bf16x8*)(lds + PG8_SB(b, h) + boff + n * 2048 + k * 1024); } while (0)
; #define PG8_MMA(ai, bj, At, Bt) do { __builtin_amdgcn_s_setprio(3); _Pragma("unroll") for (int m = 0; m < 4; ++m) _Pragma("unroll") for (int n = 0; n < 2; ++n) _Pragma("unroll") for (int k = 0; k < 2; ++k) \
;         acc[ai][bj][m][n] = __builtin_amdgcn_mfma_f32_16x16x32_bf16(Bt[n][k], At[m][k], acc[ai][bj][m][n], 0, 0, 0); __builtin_amdgcn_s_setprio(0); } while (0)
; #define PG8_WAIT_V(n) asm volatile("s_waitcnt vmcnt(" #n ")" ::: "memory")
; #define PG8_WAIT_L(n) asm volatile("s_waitcnt lgkmcnt(" #n ")" ::: "memory")
; #define PG8_BAR __builtin_amdgcn_s_barrier()
; #define PG8_SCHED __builtin_amdgcn_sched_barrier(0)
; template <class Epi, class Sched, bool ALIGN_EPI = false, bool SP2 = false>
; __device__ __forceinline__ void gemm_phase(LAS unsigned char* lds, const Gemm g, const Sched& S, const Epi& E) {
;     ...
;             PG8_LDB(B0, 1, 0); PG8_LDB(B1, 1, 1); PG8_SCHED; PG8_LDA(At, 1, 0); PG8_STAGE(PG8_SA(0, 1), a2 + hsA, voffA);
;             PG8_WAIT_V(8); PG8_WAIT_L(0); PG8_BAR; PG8_MMA(0, 0, At, B0); PG8_MMA(0, 1, At, B1); PG8_BAR; PG8_SCHED;
;             PG8_LDA(At, 1, 1); PG8_STAGE(PG8_SB(1, 0), b3, voffB); PG8_STAGE(PG8_SB(1, 1), b3 + hsB, voffB); PG8_STAGE(PG8_SA(1, 0), a3, voffA);
;             PG8_WAIT_V(8); PG8_WAIT_L(0); PG8_BAR; PG8_MMA(1, 0, At, B0); PG8_MMA(1, 1, At, B1); PG8_BAR; PG8_SCHED;
	s_add_i32 s74, 0, 0x18000
	s_add_i32 s75, 0, 0x1c000
	v_add_u32_e32 v140, s74, v173
	v_xor_b32_e32 v253, 64, v140
	v_add_u32_e32 v188, s75, v173
	v_xor_b32_e32 v254, 64, v188
	ds_read_b128 v[112:115], v140
	ds_read_b128 v[132:135], v253
	ds_read_b128 v[136:139], v140 offset:2048
	ds_read_b128 v[140:143], v253 offset:2048
	ds_read_b128 v[144:147], v188
	ds_read_b128 v[148:151], v254
	ds_read_b128 v[184:187], v188 offset:2048
	ds_read_b128 v[188:191], v254 offset:2048
	s_mov_b32 m0, s36
	s_nop 0
	global_load_lds_dwordx4 v152, s[26:27]
	s_mov_b32 m0, s37
	s_nop 0
	global_load_lds_dwordx4 v156, s[26:27]
	s_add_u32 s26, s26, 0x104000
	s_addc_u32 s27, s27, 0
	s_mov_b32 m0, s38
	ds_read_b128 v[192:195], v177 offset:32768
	ds_read_b128 v[196:199], v250 offset:32768
	ds_read_b128 v[206:209], v177 offset:34816
	ds_read_b128 v[210:213], v250 offset:34816
	ds_read_b128 v[214:217], v177 offset:36864
	ds_read_b128 v[218:221], v250 offset:36864
	ds_read_b128 v[222:225], v177 offset:38912
	ds_read_b128 v[226:229], v250 offset:38912
	global_load_lds_dwordx4 v152, s[26:27]
	s_mov_b32 m0, s39
	s_nop 0
	global_load_lds_dwordx4 v156, s[26:27]
	s_waitcnt vmcnt(8)
	s_waitcnt lgkmcnt(0)
	s_barrier
	s_setprio 3
	s_waitcnt lgkmcnt(0)
	v_mfma_f32_16x16x32_bf16 v[128:131], v[112:115], v[192:195], v[128:131]
	v_mfma_f32_16x16x32_bf16 v[128:131], v[132:135], v[196:199], v[128:131]
	v_mfma_f32_16x16x32_bf16 v[124:127], v[136:139], v[192:195], v[124:127]
	v_mfma_f32_16x16x32_bf16 v[124:127], v[140:143], v[196:199], v[124:127]
	v_mfma_f32_16x16x32_bf16 v[108:111], v[112:115], v[206:209], v[108:111]
	v_mfma_f32_16x16x32_bf16 v[108:111], v[132:135], v[210:213], v[108:111]
	v_mfma_f32_16x16x32_bf16 v[104:107], v[136:139], v[206:209], v[104:107]
	v_mfma_f32_16x16x32_bf16 v[104:107], v[140:143], v[210:213], v[104:107]
	v_mfma_f32_16x16x32_bf16 v[92:95], v[112:115], v[214:217], v[92:95]
	v_mfma_f32_16x16x32_bf16 v[92:95], v[132:135], v[218:221], v[92:95]
	v_mfma_f32_16x16x32_bf16 v[88:91], v[136:139], v[214:217], v[88:91]
	v_mfma_f32_16x16x32_bf16 v[88:91], v[140:143], v[218:221], v[88:91]
	v_mfma_f32_16x16x32_bf16 v[76:79], v[112:115], v[222:225], v[76:79]
	v_mfma_f32_16x16x32_bf16 v[76:79], v[132:135], v[226:229], v[76:79]
	v_mfma_f32_16x16x32_bf16 v[72:75], v[136:139], v[222:225], v[72:75]
	v_mfma_f32_16x16x32_bf16 v[72:75], v[140:143], v[226:229], v[72:75]
	s_setprio 0
	s_setprio 3
	v_mfma_f32_16x16x32_bf16 v[120:123], v[144:147], v[192:195], v[120:123]
	v_mfma_f32_16x16x32_bf16 v[120:123], v[148:151], v[196:199], v[120:123]
	v_mfma_f32_16x16x32_bf16 v[116:119], v[184:187], v[192:195], v[116:119]
	v_mfma_f32_16x16x32_bf16 v[116:119], v[188:191], v[196:199], v[116:119]
	v_mfma_f32_16x16x32_bf16 v[100:103], v[144:147], v[206:209], v[100:103]
	v_mfma_f32_16x16x32_bf16 v[100:103], v[148:151], v[210:213], v[100:103]
	v_mfma_f32_16x16x32_bf16 v[96:99], v[184:187], v[206:209], v[96:99]
	v_mfma_f32_16x16x32_bf16 v[96:99], v[188:191], v[210:213], v[96:99]
	v_mfma_f32_16x16x32_bf16 v[84:87], v[144:147], v[214:217], v[84:87]
	v_mfma_f32_16x16x32_bf16 v[84:87], v[148:151], v[218:221], v[84:87]
	v_mfma_f32_16x16x32_bf16 v[80:83], v[184:187], v[214:217], v[80:83]
	v_mfma_f32_16x16x32_bf16 v[80:83], v[188:191], v[218:221], v[80:83]
	v_mfma_f32_16x16x32_bf16 v[68:71], v[144:147], v[222:225], v[68:71]
	v_mfma_f32_16x16x32_bf16 v[68:71], v[148:151], v[226:229], v[68:71]
	v_mfma_f32_16x16x32_bf16 v[64:67], v[184:187], v[222:225], v[64:67]
	v_mfma_f32_16x16x32_bf16 v[64:67], v[188:191], v[226:229], v[64:67]
	s_setprio 0
	s_barrier
	s_add_i32 s26, s74, s31
	s_add_u32 s100, s24, s14
	s_addc_u32 s101, s25, s15
	s_mov_b32 m0, s26
	ds_read_b128 v[192:195], v177 offset:49152
	ds_read_b128 v[196:199], v250 offset:49152
	ds_read_b128 v[206:209], v177 offset:51200
	ds_read_b128 v[210:213], v250 offset:51200
	ds_read_b128 v[214:217], v177 offset:53248
	ds_read_b128 v[218:221], v250 offset:53248
	ds_read_b128 v[222:225], v177 offset:55296
	ds_read_b128 v[226:229], v250 offset:55296
	global_load_lds_dwordx4 v154, s[100:101]
	s_add_i32 m0, s26, 0x2000
	s_add_u32 s24, s24, 0x41080
	s_addc_u32 s25, s25, 0
	s_add_i32 s26, s75, s31
	global_load_lds_dwordx4 v158, s[100:101]
	s_mov_b32 m0, s26
	s_nop 0
	global_load_lds_dwordx4 v154, s[24:25]
	s_add_i32 m0, s26, 0x2000
	s_nop 0
	global_load_lds_dwordx4 v158, s[24:25]
	s_waitcnt vmcnt(6)
	s_waitcnt lgkmcnt(0)
	s_barrier
	s_setprio 3
	s_waitcnt lgkmcnt(0)
	v_mfma_f32_16x16x32_bf16 v[60:63], v[112:115], v[192:195], v[60:63]
	v_mfma_f32_16x16x32_bf16 v[60:63], v[132:135], v[196:199], v[60:63]
	v_mfma_f32_16x16x32_bf16 v[56:59], v[136:139], v[192:195], v[56:59]
	v_mfma_f32_16x16x32_bf16 v[56:59], v[140:143], v[196:199], v[56:59]
	v_mfma_f32_16x16x32_bf16 v[44:47], v[112:115], v[206:209], v[44:47]
	v_mfma_f32_16x16x32_bf16 v[44:47], v[132:135], v[210:213], v[44:47]
	v_mfma_f32_16x16x32_bf16 v[40:43], v[136:139], v[206:209], v[40:43]
	v_mfma_f32_16x16x32_bf16 v[40:43], v[140:143], v[210:213], v[40:43]
	v_mfma_f32_16x16x32_bf16 v[28:31], v[112:115], v[214:217], v[28:31]
	v_mfma_f32_16x16x32_bf16 v[28:31], v[132:135], v[218:221], v[28:31]
	v_mfma_f32_16x16x32_bf16 v[24:27], v[136:139], v[214:217], v[24:27]
	v_mfma_f32_16x16x32_bf16 v[24:27], v[140:143], v[218:221], v[24:27]
	v_mfma_f32_16x16x32_bf16 v[12:15], v[112:115], v[222:225], v[12:15]
	v_mfma_f32_16x16x32_bf16 v[12:15], v[132:135], v[226:229], v[12:15]
	v_mfma_f32_16x16x32_bf16 v[8:11], v[136:139], v[222:225], v[8:11]
	v_mfma_f32_16x16x32_bf16 v[8:11], v[140:143], v[226:229], v[8:11]
	s_setprio 0
	s_setprio 3
	v_mfma_f32_16x16x32_bf16 v[52:55], v[144:147], v[192:195], v[52:55]
	v_mfma_f32_16x16x32_bf16 v[52:55], v[148:151], v[196:199], v[52:55]
	v_mfma_f32_16x16x32_bf16 v[48:51], v[184:187], v[192:195], v[48:51]
	v_mfma_f32_16x16x32_bf16 v[48:51], v[188:191], v[196:199], v[48:51]
	v_mfma_f32_16x16x32_bf16 v[36:39], v[144:147], v[206:209], v[36:39]
	v_mfma_f32_16x16x32_bf16 v[36:39], v[148:151], v[210:213], v[36:39]
	v_mfma_f32_16x16x32_bf16 v[32:35], v[184:187], v[206:209], v[32:35]
	v_mfma_f32_16x16x32_bf16 v[32:35], v[188:191], v[210:213], v[32:35]
	v_mfma_f32_16x16x32_bf16 v[20:23], v[144:147], v[214:217], v[20:23]
	v_mfma_f32_16x16x32_bf16 v[20:23], v[148:151], v[218:221], v[20:23]
	v_mfma_f32_16x16x32_bf16 v[16:19], v[184:187], v[214:217], v[16:19]
	v_mfma_f32_16x16x32_bf16 v[16:19], v[188:191], v[218:221], v[16:19]
	v_mfma_f32_16x16x32_bf16 v[4:7], v[144:147], v[222:225], v[4:7]
	v_mfma_f32_16x16x32_bf16 v[4:7], v[148:151], v[226:229], v[4:7]
	v_mfma_f32_16x16x32_bf16 v[0:3], v[184:187], v[222:225], v[0:3]
	v_mfma_f32_16x16x32_bf16 v[0:3], v[188:191], v[226:229], v[0:3]
	s_setprio 0
	s_barrier
	s_add_i32 s73, s73, 2
	s_add_u32 s4, s4, 0x100
	s_addc_u32 s5, s5, 0
	s_add_u32 s71, s71, 0x100
	s_addc_u32 s72, s72, 0
	s_cmp_gt_u32 s73, 61
	s_cbranch_scc0 .LBB0_309
	s_and_b64 vcc, exec, s[16:17]
	s_cbranch_vccz .LBB0_312
	s_barrier

; #define PG8_STAGE(bufoff, gbase, voff) do { _Pragma("unroll") for (int _i = 0; _i < 2; ++_i) \
;         __builtin_amdgcn_global_load_lds((const unsigned*)((const char*)(gbase) + (voff)[_i]), (LAS unsigned*)(lds + (bufoff) + ldsw + _i * 8192), 16, 0, 0); } while (0)
; #define PG8_LDA(dst, b, h) do { _Pragma("unroll") for (int m = 0; m < 4; ++m) _Pragma("unroll") for (int k = 0; k < 2; ++k) dst[m][k] = *(const LAS bf16x8*)(lds + PG8_SA(b, h) + aoff + m * 2048 + k * 1024); } while (0)
; #define PG8_LDB(dst, b, h) do { _Pragma("unroll") for (int n = 0; n < 2; ++n) _Pragma("unroll") for (int k = 0; k < 2; ++k) dst[n][k] = *(const LAS bf16x8*)(lds + PG8_SB(b, h) + boff + n * 2048 + k * 1024); } while (0)
; #define PG8_MMA(ai, bj, At, Bt) do { __builtin_amdgcn_s_setprio(3); _Pragma("unroll") for (int m = 0; m < 4; ++m) _Pragma("unroll") for (int n = 0; n < 2; ++n) _Pragma("unroll") for (int k = 0; k < 2; ++k) \
;         acc[ai][bj][m][n] = __builtin_amdgcn_mfma_f32_16x16x32_bf16(Bt[n][k], At[m][k], acc[ai][bj][m][n], 0, 0, 0); __builtin_amdgcn_s_setprio(0); } while (0)
; #define PG8_WAIT_V(n) asm volatile("s_waitcnt vmcnt(" #n ")" ::: "memory")
; #define PG8_WAIT_L(n) asm volatile("s_waitcnt lgkmcnt(" #n ")" ::: "memory")
; #define PG8_BAR __builtin_amdgcn_s_barrier()
; template <class Epi, class Sched, bool ALIGN_EPI = false, bool SP2 = false>
; __device__ __forceinline__ void gemm_phase(LAS unsigned char* lds, const Gemm g, const Sched& S, const Epi& E) {
;     ...
;             const char* a2 = last ? nA : cA + (size_t)(t + 2) * kstep; const char* b2 = last ? nB : cB + (size_t)(t + 2) * kstep;
;             const char* a3 = a2 + kstep; const char* b3 = b2 + kstep;
;             if (last && has_next) S.a_ready(nxt);
;             if constexpr (Epi::MID) { if (t == nt / 2) E.mid(acc, cur, wr, wc, fr, fq); }
;             if constexpr (SP2) {
;             PG8_LDB(B0, 0, 0); PG8_LDB(B1, 0, 1); PG8_SCHED; PG8_LDA(At, 0, 0); PG8_STAGE(PG8_SA(1, 1), a1 + hsA, voffA);
;             PG8_WAIT_V(8); PG8_WAIT_L(0); PG8_BAR; PG8_MMA(0, 0, At, B0); PG8_MMA(0, 1, At, B1); PG8_BAR; PG8_SCHED;
;             PG8_LDA(At, 0, 1); PG8_STAGE(PG8_SB(0, 0), b2, voffB); PG8_STAGE(PG8_SB(0, 1), b2 + hsB, voffB); PG8_STAGE(PG8_SA(0, 0), a2, voffA);
;             PG8_WAIT_V(8); PG8_WAIT_L(0); PG8_BAR; PG8_MMA(1, 0, At, B0); PG8_MMA(1, 1, At, B1); PG8_BAR; PG8_SCHED;
.LBB0_350:
	ds_read_b128 v[140:143], v149
	ds_read_b128 v[156:159], v251
	ds_read_b128 v[160:163], v149 offset:2048
	ds_read_b128 v[164:167], v251 offset:2048
	ds_read_b128 v[168:171], v150
	ds_read_b128 v[172:175], v252
	ds_read_b128 v[176:179], v150 offset:2048
	ds_read_b128 v[180:183], v252 offset:2048
	s_add_u32 s16, s14, 0xffbfc080
	s_addc_u32 s17, s15, -1
	s_cmpk_eq_i32 s50, 0xfc
	s_cselect_b32 s21, s5, s17
	s_cselect_b32 s20, s4, s16
	s_cselect_b32 s17, s13, s49
	s_cselect_b32 s16, s12, s48
	s_sub_u32 s100, s14, 0x404000
	s_subb_u32 s101, s15, 0
	s_mov_b32 m0, s33
	s_nop 0
	global_load_lds_dwordx4 v128, s[100:101]
	s_mov_b32 m0, s38
	s_nop 0
	global_load_lds_dwordx4 v130, s[100:101]
	s_add_i32 m0, s26, 0xc000
	ds_read_b128 v[184:187], v151
	ds_read_b128 v[188:191], v250
	ds_read_b128 v[192:195], v151 offset:2048
	ds_read_b128 v[196:199], v250 offset:2048
	ds_read_b128 v[200:203], v151 offset:4096
	ds_read_b128 v[204:207], v250 offset:4096
	ds_read_b128 v[208:211], v151 offset:6144
	ds_read_b128 v[212:215], v250 offset:6144
	global_load_lds_dwordx4 v132, s[14:15]
	s_add_i32 m0, s26, 0xe000
	s_nop 0
	global_load_lds_dwordx4 v134, s[14:15]
	s_waitcnt vmcnt(8)
	s_waitcnt lgkmcnt(0)
	s_barrier
	s_setprio 3
	s_waitcnt lgkmcnt(0)
	v_mfma_f32_16x16x32_bf16 v[124:127], v[140:143], v[184:187], v[124:127]
	v_mfma_f32_16x16x32_bf16 v[124:127], v[156:159], v[188:191], v[124:127]
	v_mfma_f32_16x16x32_bf16 v[120:123], v[160:163], v[184:187], v[120:123]
	v_mfma_f32_16x16x32_bf16 v[120:123], v[164:167], v[188:191], v[120:123]
	v_mfma_f32_16x16x32_bf16 v[108:111], v[140:143], v[192:195], v[108:111]
	v_mfma_f32_16x16x32_bf16 v[108:111], v[156:159], v[196:199], v[108:111]
	v_mfma_f32_16x16x32_bf16 v[104:107], v[160:163], v[192:195], v[104:107]
	v_mfma_f32_16x16x32_bf16 v[104:107], v[164:167], v[196:199], v[104:107]
	v_mfma_f32_16x16x32_bf16 v[92:95], v[140:143], v[200:203], v[92:95]
	v_mfma_f32_16x16x32_bf16 v[92:95], v[156:159], v[204:207], v[92:95]
	v_mfma_f32_16x16x32_bf16 v[88:91], v[160:163], v[200:203], v[88:91]
	v_mfma_f32_16x16x32_bf16 v[88:91], v[164:167], v[204:207], v[88:91]
	v_mfma_f32_16x16x32_bf16 v[76:79], v[140:143], v[208:211], v[76:79]
	v_mfma_f32_16x16x32_bf16 v[76:79], v[156:159], v[212:215], v[76:79]
	v_mfma_f32_16x16x32_bf16 v[72:75], v[160:163], v[208:211], v[72:75]
	v_mfma_f32_16x16x32_bf16 v[72:75], v[164:167], v[212:215], v[72:75]
	s_setprio 0
	s_setprio 3
	v_mfma_f32_16x16x32_bf16 v[116:119], v[168:171], v[184:187], v[116:119]
	v_mfma_f32_16x16x32_bf16 v[116:119], v[172:175], v[188:191], v[116:119]
	v_mfma_f32_16x16x32_bf16 v[112:115], v[176:179], v[184:187], v[112:115]
	v_mfma_f32_16x16x32_bf16 v[112:115], v[180:183], v[188:191], v[112:115]
	v_mfma_f32_16x16x32_bf16 v[100:103], v[168:171], v[192:195], v[100:103]
	v_mfma_f32_16x16x32_bf16 v[100:103], v[172:175], v[196:199], v[100:103]
	v_mfma_f32_16x16x32_bf16 v[96:99], v[176:179], v[192:195], v[96:99]
	v_mfma_f32_16x16x32_bf16 v[96:99], v[180:183], v[196:199], v[96:99]
	v_mfma_f32_16x16x32_bf16 v[84:87], v[168:171], v[200:203], v[84:87]
	v_mfma_f32_16x16x32_bf16 v[84:87], v[172:175], v[204:207], v[84:87]
	v_mfma_f32_16x16x32_bf16 v[80:83], v[176:179], v[200:203], v[80:83]
	v_mfma_f32_16x16x32_bf16 v[80:83], v[180:183], v[204:207], v[80:83]
	v_mfma_f32_16x16x32_bf16 v[68:71], v[168:171], v[208:211], v[68:71]
	v_mfma_f32_16x16x32_bf16 v[68:71], v[172:175], v[212:215], v[68:71]
	v_mfma_f32_16x16x32_bf16 v[64:67], v[176:179], v[208:211], v[64:67]
	v_mfma_f32_16x16x32_bf16 v[64:67], v[180:183], v[212:215], v[64:67]
	s_setprio 0
	s_barrier
	s_add_i32 s51, s41, s25
	s_mov_b32 m0, s51
	ds_read_b128 v[184:187], v151 offset:16384
	ds_read_b128 v[188:191], v250 offset:16384
	ds_read_b128 v[192:195], v151 offset:18432
	ds_read_b128 v[196:199], v250 offset:18432
	ds_read_b128 v[200:203], v151 offset:20480
	ds_read_b128 v[204:207], v250 offset:20480
	ds_read_b128 v[208:211], v151 offset:22528
	ds_read_b128 v[212:215], v250 offset:22528
	global_load_lds_dwordx4 v128, s[16:17]
	s_add_i32 m0, s51, 0x2000
	s_add_u32 s52, s16, 0x404000
	s_addc_u32 s53, s17, 0
	s_add_i32 s51, s42, s25
	global_load_lds_dwordx4 v130, s[16:17]
	s_mov_b32 m0, s51
	s_nop 0
	global_load_lds_dwordx4 v128, s[52:53]
	s_add_i32 m0, s51, 0x2000
	s_nop 0
	global_load_lds_dwordx4 v130, s[52:53]
	s_waitcnt vmcnt(6)
	s_waitcnt lgkmcnt(0)
	s_barrier
	s_setprio 3
	s_waitcnt lgkmcnt(0)
	v_mfma_f32_16x16x32_bf16 v[60:63], v[140:143], v[184:187], v[60:63]
	v_mfma_f32_16x16x32_bf16 v[60:63], v[156:159], v[188:191], v[60:63]
	v_mfma_f32_16x16x32_bf16 v[56:59], v[160:163], v[184:187], v[56:59]
	v_mfma_f32_16x16x32_bf16 v[56:59], v[164:167], v[188:191], v[56:59]
	v_mfma_f32_16x16x32_bf16 v[44:47], v[140:143], v[192:195], v[44:47]
	v_mfma_f32_16x16x32_bf16 v[44:47], v[156:159], v[196:199], v[44:47]
	v_mfma_f32_16x16x32_bf16 v[40:43], v[160:163], v[192:195], v[40:43]
	v_mfma_f32_16x16x32_bf16 v[40:43], v[164:167], v[196:199], v[40:43]
	v_mfma_f32_16x16x32_bf16 v[28:31], v[140:143], v[200:203], v[28:31]
	v_mfma_f32_16x16x32_bf16 v[28:31], v[156:159], v[204:207], v[28:31]
	v_mfma_f32_16x16x32_bf16 v[24:27], v[160:163], v[200:203], v[24:27]
	v_mfma_f32_16x16x32_bf16 v[24:27], v[164:167], v[204:207], v[24:27]
	v_mfma_f32_16x16x32_bf16 v[12:15], v[140:143], v[208:211], v[12:15]
	v_mfma_f32_16x16x32_bf16 v[12:15], v[156:159], v[212:215], v[12:15]
	v_mfma_f32_16x16x32_bf16 v[8:11], v[160:163], v[208:211], v[8:11]
	v_mfma_f32_16x16x32_bf16 v[8:11], v[164:167], v[212:215], v[8:11]
	s_setprio 0
	s_setprio 3
	v_mfma_f32_16x16x32_bf16 v[52:55], v[168:171], v[184:187], v[52:55]
	v_mfma_f32_16x16x32_bf16 v[52:55], v[172:175], v[188:191], v[52:55]
	v_mfma_f32_16x16x32_bf16 v[48:51], v[176:179], v[184:187], v[48:51]
	v_mfma_f32_16x16x32_bf16 v[48:51], v[180:183], v[188:191], v[48:51]
	v_mfma_f32_16x16x32_bf16 v[36:39], v[168:171], v[192:195], v[36:39]
	v_mfma_f32_16x16x32_bf16 v[36:39], v[172:175], v[196:199], v[36:39]
	v_mfma_f32_16x16x32_bf16 v[32:35], v[176:179], v[192:195], v[32:35]
	v_mfma_f32_16x16x32_bf16 v[32:35], v[180:183], v[196:199], v[32:35]
	v_mfma_f32_16x16x32_bf16 v[20:23], v[168:171], v[200:203], v[20:23]
	v_mfma_f32_16x16x32_bf16 v[20:23], v[172:175], v[204:207], v[20:23]
	v_mfma_f32_16x16x32_bf16 v[16:19], v[176:179], v[200:203], v[16:19]
	v_mfma_f32_16x16x32_bf16 v[16:19], v[180:183], v[204:207], v[16:19]
	v_mfma_f32_16x16x32_bf16 v[4:7], v[168:171], v[208:211], v[4:7]
	v_mfma_f32_16x16x32_bf16 v[4:7], v[172:175], v[212:215], v[4:7]
	v_mfma_f32_16x16x32_bf16 v[0:3], v[176:179], v[208:211], v[0:3]
	v_mfma_f32_16x16x32_bf16 v[0:3], v[180:183], v[212:215], v[0:3]
	s_setprio 0
	s_barrier
; #define PG8_STAGE(bufoff, gbase, voff) do { _Pragma("unroll") for (int _i = 0; _i < 2; ++_i) \
;         __builtin_amdgcn_global_load_lds((const unsigned*)((const char*)(gbase) + (voff)[_i]), (LAS unsigned*)(lds + (bufoff) + ldsw + _i * 8192), 16, 0, 0); } while (0)
; #define PG8_LDA(dst, b, h) do { _Pragma("unroll") for (int m = 0; m < 4; ++m) _Pragma("unroll") for (int k = 0; k < 2; ++k) dst[m][k] = *(const LAS bf16x8*)(lds + PG8_SA(b, h) + aoff + m * 2048 + k * 1024); } while (0)
; #define PG8_LDB(dst, b, h) do { _Pragma("unroll") for (int n = 0; n < 2; ++n) _Pragma("unroll") for (int k = 0; k < 2; ++k) dst[n][k] = *(const LAS bf16x8*)(lds + PG8_SB(b, h) + boff + n * 2048 + k * 1024); } while (0)
; #define PG8_MMA(ai, bj, At, Bt) do { __builtin_amdgcn_s_setprio(3); _Pragma("unroll") for (int m = 0; m < 4; ++m) _Pragma("unroll") for (int n = 0; n < 2; ++n) _Pragma("unroll") for (int k = 0; k < 2; ++k) \
;         acc[ai][bj][m][n] = __builtin_amdgcn_mfma_f32_16x16x32_bf16(Bt[n][k], At[m][k], acc[ai][bj][m][n], 0, 0, 0); __builtin_amdgcn_s_setprio(0); } while (0)
; #define PG8_WAIT_V(n) asm volatile("s_waitcnt vmcnt(" #n ")" ::: "memory")
; #define PG8_WAIT_L(n) asm volatile("s_waitcnt lgkmcnt(" #n ")" ::: "memory")
; #define PG8_BAR __builtin_amdgcn_s_barrier()
; #define PG8_SCHED __builtin_amdgcn_sched_barrier(0)
; template <class Epi, class Sched, bool ALIGN_EPI = false, bool SP2 = false>
; __device__ __forceinline__ void gemm_phase(LAS unsigned char* lds, const Gemm g, const Sched& S, const Epi& E) {
;     ...
;             PG8_LDB(B0, 1, 0); PG8_LDB(B1, 1, 1); PG8_SCHED; PG8_LDA(At, 1, 0); PG8_STAGE(PG8_SA(0, 1), a2 + hsA, voffA);
;             PG8_WAIT_V(8); PG8_WAIT_L(0); PG8_BAR; PG8_MMA(0, 0, At, B0); PG8_MMA(0, 1, At, B1); PG8_BAR; PG8_SCHED;
;             PG8_LDA(At, 1, 1); PG8_STAGE(PG8_SB(1, 0), b3, voffB); PG8_STAGE(PG8_SB(1, 1), b3 + hsB, voffB); PG8_STAGE(PG8_SA(1, 0), a3, voffA);
;             PG8_WAIT_V(8); PG8_WAIT_L(0); PG8_BAR; PG8_MMA(1, 0, At, B0); PG8_MMA(1, 1, At, B1); PG8_BAR; PG8_SCHED;
	s_add_i32 s51, 0, 0x18000
	v_add_u32_e32 v155, s51, v146
	v_xor_b32_e32 v253, 64, v155
	s_add_i32 s52, 0, 0x1c000
	ds_read_b128 v[140:143], v155
	ds_read_b128 v[156:159], v253
	ds_read_b128 v[160:163], v155 offset:2048
	ds_read_b128 v[164:167], v253 offset:2048
	v_add_u32_e32 v155, s52, v146
	v_xor_b32_e32 v253, 64, v155
	ds_read_b128 v[168:171], v155
	ds_read_b128 v[172:175], v253
	ds_read_b128 v[176:179], v155 offset:2048
	ds_read_b128 v[180:183], v253 offset:2048
	s_mov_b32 m0, s26
	s_nop 0
	global_load_lds_dwordx4 v128, s[20:21]
	s_mov_b32 m0, s27
	s_nop 0
	global_load_lds_dwordx4 v130, s[20:21]
	s_add_u32 s20, s20, 0x404000
	s_addc_u32 s21, s21, 0
	s_mov_b32 m0, s30
	ds_read_b128 v[184:187], v151 offset:32768
	ds_read_b128 v[188:191], v250 offset:32768
	ds_read_b128 v[192:195], v151 offset:34816
	ds_read_b128 v[196:199], v250 offset:34816
	ds_read_b128 v[200:203], v151 offset:36864
	ds_read_b128 v[204:207], v250 offset:36864
	ds_read_b128 v[208:211], v151 offset:38912
	ds_read_b128 v[212:215], v250 offset:38912
	global_load_lds_dwordx4 v128, s[20:21]
	s_mov_b32 m0, s31
	s_nop 0
	global_load_lds_dwordx4 v130, s[20:21]
	s_waitcnt vmcnt(8)
	s_waitcnt lgkmcnt(0)
	s_barrier
	s_setprio 3
	s_waitcnt lgkmcnt(0)
	v_mfma_f32_16x16x32_bf16 v[124:127], v[140:143], v[184:187], v[124:127]
	v_mfma_f32_16x16x32_bf16 v[124:127], v[156:159], v[188:191], v[124:127]
	v_mfma_f32_16x16x32_bf16 v[120:123], v[160:163], v[184:187], v[120:123]
	v_mfma_f32_16x16x32_bf16 v[120:123], v[164:167], v[188:191], v[120:123]
	v_mfma_f32_16x16x32_bf16 v[108:111], v[140:143], v[192:195], v[108:111]
	v_mfma_f32_16x16x32_bf16 v[108:111], v[156:159], v[196:199], v[108:111]
	v_mfma_f32_16x16x32_bf16 v[104:107], v[160:163], v[192:195], v[104:107]
	v_mfma_f32_16x16x32_bf16 v[104:107], v[164:167], v[196:199], v[104:107]
	v_mfma_f32_16x16x32_bf16 v[92:95], v[140:143], v[200:203], v[92:95]
	v_mfma_f32_16x16x32_bf16 v[92:95], v[156:159], v[204:207], v[92:95]
	v_mfma_f32_16x16x32_bf16 v[88:91], v[160:163], v[200:203], v[88:91]
	v_mfma_f32_16x16x32_bf16 v[88:91], v[164:167], v[204:207], v[88:91]
	v_mfma_f32_16x16x32_bf16 v[76:79], v[140:143], v[208:211], v[76:79]
	v_mfma_f32_16x16x32_bf16 v[76:79], v[156:159], v[212:215], v[76:79]
	v_mfma_f32_16x16x32_bf16 v[72:75], v[160:163], v[208:211], v[72:75]
	v_mfma_f32_16x16x32_bf16 v[72:75], v[164:167], v[212:215], v[72:75]
	s_setprio 0
	s_setprio 3
	v_mfma_f32_16x16x32_bf16 v[116:119], v[168:171], v[184:187], v[116:119]
	v_mfma_f32_16x16x32_bf16 v[116:119], v[172:175], v[188:191], v[116:119]
	v_mfma_f32_16x16x32_bf16 v[112:115], v[176:179], v[184:187], v[112:115]
	v_mfma_f32_16x16x32_bf16 v[112:115], v[180:183], v[188:191], v[112:115]
	v_mfma_f32_16x16x32_bf16 v[100:103], v[168:171], v[192:195], v[100:103]
	v_mfma_f32_16x16x32_bf16 v[100:103], v[172:175], v[196:199], v[100:103]
	v_mfma_f32_16x16x32_bf16 v[96:99], v[176:179], v[192:195], v[96:99]
	v_mfma_f32_16x16x32_bf16 v[96:99], v[180:183], v[196:199], v[96:99]
	v_mfma_f32_16x16x32_bf16 v[84:87], v[168:171], v[200:203], v[84:87]
	v_mfma_f32_16x16x32_bf16 v[84:87], v[172:175], v[204:207], v[84:87]
	v_mfma_f32_16x16x32_bf16 v[80:83], v[176:179], v[200:203], v[80:83]
	v_mfma_f32_16x16x32_bf16 v[80:83], v[180:183], v[204:207], v[80:83]
	v_mfma_f32_16x16x32_bf16 v[68:71], v[168:171], v[208:211], v[68:71]
	v_mfma_f32_16x16x32_bf16 v[68:71], v[172:175], v[212:215], v[68:71]
	v_mfma_f32_16x16x32_bf16 v[64:67], v[176:179], v[208:211], v[64:67]
	v_mfma_f32_16x16x32_bf16 v[64:67], v[180:183], v[212:215], v[64:67]
	s_setprio 0
	s_barrier
	s_add_i32 s20, s51, s25
	s_add_u32 s100, s16, s8
	s_addc_u32 s101, s17, s9
	s_mov_b32 m0, s20
	ds_read_b128 v[184:187], v151 offset:49152
	ds_read_b128 v[188:191], v250 offset:49152
	ds_read_b128 v[192:195], v151 offset:51200
	ds_read_b128 v[196:199], v250 offset:51200
	ds_read_b128 v[200:203], v151 offset:53248
	ds_read_b128 v[204:207], v250 offset:53248
	ds_read_b128 v[208:211], v151 offset:55296
	ds_read_b128 v[212:215], v250 offset:55296
	global_load_lds_dwordx4 v128, s[100:101]
	s_add_i32 m0, s20, 0x2000
	s_add_u32 s16, s16, 0x404080
	s_addc_u32 s17, s17, 0
	s_add_i32 s20, s52, s25
	global_load_lds_dwordx4 v130, s[100:101]
	s_mov_b32 m0, s20
	s_nop 0
	global_load_lds_dwordx4 v128, s[16:17]
	s_add_i32 m0, s20, 0x2000
	s_nop 0
	global_load_lds_dwordx4 v130, s[16:17]
	s_waitcnt vmcnt(6)
	s_waitcnt lgkmcnt(0)
	s_barrier
	s_setprio 3
	s_waitcnt lgkmcnt(0)
	v_mfma_f32_16x16x32_bf16 v[60:63], v[140:143], v[184:187], v[60:63]
	v_mfma_f32_16x16x32_bf16 v[60:63], v[156:159], v[188:191], v[60:63]
	v_mfma_f32_16x16x32_bf16 v[56:59], v[160:163], v[184:187], v[56:59]
	v_mfma_f32_16x16x32_bf16 v[56:59], v[164:167], v[188:191], v[56:59]
	v_mfma_f32_16x16x32_bf16 v[44:47], v[140:143], v[192:195], v[44:47]
	v_mfma_f32_16x16x32_bf16 v[44:47], v[156:159], v[196:199], v[44:47]
	v_mfma_f32_16x16x32_bf16 v[40:43], v[160:163], v[192:195], v[40:43]
	v_mfma_f32_16x16x32_bf16 v[40:43], v[164:167], v[196:199], v[40:43]
	v_mfma_f32_16x16x32_bf16 v[28:31], v[140:143], v[200:203], v[28:31]
	v_mfma_f32_16x16x32_bf16 v[28:31], v[156:159], v[204:207], v[28:31]
	v_mfma_f32_16x16x32_bf16 v[24:27], v[160:163], v[200:203], v[24:27]
	v_mfma_f32_16x16x32_bf16 v[24:27], v[164:167], v[204:207], v[24:27]
	v_mfma_f32_16x16x32_bf16 v[12:15], v[140:143], v[208:211], v[12:15]
	v_mfma_f32_16x16x32_bf16 v[12:15], v[156:159], v[212:215], v[12:15]
	v_mfma_f32_16x16x32_bf16 v[8:11], v[160:163], v[208:211], v[8:11]
	v_mfma_f32_16x16x32_bf16 v[8:11], v[164:167], v[212:215], v[8:11]
	s_setprio 0
	s_setprio 3
	v_mfma_f32_16x16x32_bf16 v[52:55], v[168:171], v[184:187], v[52:55]
	v_mfma_f32_16x16x32_bf16 v[52:55], v[172:175], v[188:191], v[52:55]
	v_mfma_f32_16x16x32_bf16 v[48:51], v[176:179], v[184:187], v[48:51]
	v_mfma_f32_16x16x32_bf16 v[48:51], v[180:183], v[188:191], v[48:51]
	v_mfma_f32_16x16x32_bf16 v[36:39], v[168:171], v[192:195], v[36:39]
	v_mfma_f32_16x16x32_bf16 v[36:39], v[172:175], v[196:199], v[36:39]
	v_mfma_f32_16x16x32_bf16 v[32:35], v[176:179], v[192:195], v[32:35]
	v_mfma_f32_16x16x32_bf16 v[32:35], v[180:183], v[196:199], v[32:35]
	v_mfma_f32_16x16x32_bf16 v[20:23], v[168:171], v[200:203], v[20:23]
	v_mfma_f32_16x16x32_bf16 v[20:23], v[172:175], v[204:207], v[20:23]
	v_mfma_f32_16x16x32_bf16 v[16:19], v[176:179], v[200:203], v[16:19]
	v_mfma_f32_16x16x32_bf16 v[16:19], v[180:183], v[204:207], v[16:19]
	v_mfma_f32_16x16x32_bf16 v[4:7], v[168:171], v[208:211], v[4:7]
	v_mfma_f32_16x16x32_bf16 v[4:7], v[172:175], v[212:215], v[4:7]
	v_mfma_f32_16x16x32_bf16 v[0:3], v[176:179], v[208:211], v[0:3]
	v_mfma_f32_16x16x32_bf16 v[0:3], v[180:183], v[212:215], v[0:3]
	s_setprio 0
	s_barrier
	s_add_i32 s50, s50, 2
	s_add_u32 s14, s14, 0x100
	s_addc_u32 s15, s15, 0
	s_add_u32 s48, s48, 0x100
	s_addc_u32 s49, s49, 0
	s_cmpk_gt_u32 s50, 0xfd
	s_cbranch_scc0 .LBB0_350
	s_and_b64 vcc, exec, s[10:11]
	s_cbranch_vccz .LBB0_353
	s_barrier
